# attention: DMA address arithmetic moved into the matrix segment, row-sum check before the last conversions
# speedup vs baseline: 1.0142x; 1.0034x over previous
.Lattn_tb1:
	s_waitcnt lgkmcnt(5)
	v_mfma_f32_32x32x16_bf16 v[96:111], v[208:211], v[128:131], 0
	ds_read_b128 v[208:211], v185 offset:16384
	s_add_i32 s2, s42, 4
	s_and_b32 s2, s2, 31
	s_waitcnt lgkmcnt(5)
	v_mfma_f32_32x32x16_bf16 v[112:127], v[212:215], v[128:131], 0
	ds_read_b128 v[212:215], v185 offset:20480
	s_mul_i32 s2, s2, 0x44000
	s_add_u32 s48, s26, s2
	s_waitcnt lgkmcnt(5)
	v_mfma_f32_32x32x16_bf16 v[96:111], v[216:219], v[132:135], v[96:111]
	s_addc_u32 s49, s27, 0
	s_add_u32 s50, s48, 0x80
	s_waitcnt lgkmcnt(4)
	v_mfma_f32_32x32x16_bf16 v[112:127], v[220:223], v[132:135], v[112:127]
	s_addc_u32 s51, s49, 0
	s_add_i32 s2, s42, 2
	s_waitcnt lgkmcnt(3)
	v_mfma_f32_32x32x16_bf16 v[96:111], v[224:227], v[136:139], v[96:111]
	s_and_b32 s2, s2, 31
	s_lshl_b32 s2, s2, 7
	s_waitcnt lgkmcnt(2)
	v_mfma_f32_32x32x16_bf16 v[112:127], v[228:231], v[136:139], v[112:127]
	s_add_u32 s52, s10, s2
	s_addc_u32 s53, s11, 0
	s_waitcnt lgkmcnt(1)
	v_mfma_f32_32x32x16_bf16 v[96:111], v[208:211], v[140:143], v[96:111]
	s_add_u32 s54, s52, 0x204000
	s_addc_u32 s55, s53, 0
	s_waitcnt lgkmcnt(0)
	v_mfma_f32_32x32x16_bf16 v[112:127], v[212:215], v[140:143], v[112:127]
	s_cmp_lg_u32 s14, 0
	s_cbranch_scc0 .Lattn_tb2
	s_barrier
.Lattn_tb2:
	ds_read_b128 v[216:219], v187 offset:0
	ds_read_b128 v[220:223], v187 offset:4096
	ds_read_b128 v[224:227], v187 offset:8192
	ds_read_b128 v[228:231], v187 offset:12288
	ds_read_b128 v[208:211], v188 offset:0
	ds_read_b128 v[212:215], v188 offset:4096
	v_max3_f32 v254, v64, v65, v66
	s_add_i32 m0, s5, 0
	v_max3_f32 v255, v80, v81, v82
	global_load_lds_dwordx4 v170, s[48:49]
	v_max3_f32 v254, v254, v67, v68
	s_add_i32 m0, s5, 8192
	v_max3_f32 v255, v255, v83, v84
	global_load_lds_dwordx4 v170, s[50:51]
	v_max3_f32 v254, v254, v69, v70
	s_add_i32 m0, s5, 98304
	v_max3_f32 v255, v255, v85, v86
	global_load_lds_dwordx4 v172, s[52:53]
	v_max3_f32 v254, v254, v71, v72
	s_add_i32 m0, s5, 106496
	v_max3_f32 v255, v255, v87, v88
	global_load_lds_dwordx4 v172, s[54:55]
	v_max3_f32 v254, v254, v73, v74
	v_max3_f32 v255, v255, v89, v90
	v_max3_f32 v254, v254, v75, v76
	v_max3_f32 v255, v255, v91, v92
	v_max3_f32 v254, v254, v77, v78
	v_max3_f32 v255, v255, v93, v94
	v_max3_f32 v254, v254, v79, v95
	v_max_f32_e32 v254, v254, v255
	v_mov_b32_e32 v180, 0xc2800000
	v_cmp_lt_f32_e32 vcc, 0x4138aa3b, v254
	v_cmp_gt_f32_e64 s[40:41], v180, v254
	s_nop 4
	s_or_b64 vcc, vcc, s[40:41]
	s_nop 0
	s_cbranch_vccnz .Lattn_sp_t0
	v_exp_f32_e32 v64, v64
	v_exp_f32_e32 v65, v65
	v_exp_f32_e32 v66, v66
	v_exp_f32_e32 v67, v67
	v_exp_f32_e32 v68, v68
	v_exp_f32_e32 v69, v69
	v_exp_f32_e32 v70, v70
	v_exp_f32_e32 v71, v71
	v_add_f32_e32 v190, v64, v65
	v_add_f32_e32 v191, v66, v67
	v_add_f32_e32 v190, v190, v68
	v_add_f32_e32 v191, v191, v69
	v_add_f32_e32 v190, v190, v70
	v_add_f32_e32 v191, v191, v71
	v_cvt_pk_bf16_f32 v144, v64, v65
	v_cvt_pk_bf16_f32 v145, v66, v67
	v_cvt_pk_bf16_f32 v146, v68, v69
	v_cvt_pk_bf16_f32 v147, v70, v71
	v_exp_f32_e32 v72, v72
	v_exp_f32_e32 v73, v73
	v_exp_f32_e32 v74, v74
	v_exp_f32_e32 v75, v75
	v_exp_f32_e32 v76, v76
	v_exp_f32_e32 v77, v77
	v_exp_f32_e32 v78, v78
	v_exp_f32_e32 v79, v79
	v_add_f32_e32 v190, v190, v72
	v_add_f32_e32 v191, v191, v73
	v_add_f32_e32 v190, v190, v74
	v_add_f32_e32 v191, v191, v75
	v_add_f32_e32 v190, v190, v76
	v_add_f32_e32 v191, v191, v77
	v_add_f32_e32 v190, v190, v78
	v_add_f32_e32 v191, v191, v79
	v_cvt_pk_bf16_f32 v148, v72, v73
	v_cvt_pk_bf16_f32 v149, v74, v75
	v_cvt_pk_bf16_f32 v150, v76, v77
	v_cvt_pk_bf16_f32 v151, v78, v79
	v_exp_f32_e32 v80, v80
	v_exp_f32_e32 v81, v81
	v_exp_f32_e32 v82, v82
	v_exp_f32_e32 v83, v83
	v_exp_f32_e32 v84, v84
	v_exp_f32_e32 v85, v85
	v_exp_f32_e32 v86, v86
	v_exp_f32_e32 v87, v87
	v_add_f32_e32 v190, v190, v80
	v_add_f32_e32 v191, v191, v81
	v_add_f32_e32 v190, v190, v82
	v_add_f32_e32 v191, v191, v83
	v_add_f32_e32 v190, v190, v84
	v_add_f32_e32 v191, v191, v85
	v_add_f32_e32 v190, v190, v86
	v_add_f32_e32 v191, v191, v87
	v_cvt_pk_bf16_f32 v152, v80, v81
	v_cvt_pk_bf16_f32 v153, v82, v83
	v_cvt_pk_bf16_f32 v154, v84, v85
	v_cvt_pk_bf16_f32 v155, v86, v87
	v_exp_f32_e32 v88, v88
	v_exp_f32_e32 v89, v89
	v_exp_f32_e32 v90, v90
	v_exp_f32_e32 v91, v91
	v_exp_f32_e32 v92, v92
	v_exp_f32_e32 v93, v93
	v_exp_f32_e32 v94, v94
	v_exp_f32_e32 v95, v95
	v_add_f32_e32 v190, v190, v88
	v_add_f32_e32 v191, v191, v89
	v_add_f32_e32 v190, v190, v90
	v_add_f32_e32 v191, v191, v91
	v_add_f32_e32 v190, v190, v92
	v_add_f32_e32 v191, v191, v93
	v_add_f32_e32 v190, v190, v94
	v_add_f32_e32 v191, v191, v95
	v_cvt_pk_bf16_f32 v156, v88, v89
	v_cvt_pk_bf16_f32 v157, v90, v91
	v_cvt_pk_bf16_f32 v158, v92, v93
	v_cvt_pk_bf16_f32 v159, v94, v95
	v_add_f32_e32 v190, v190, v191
	v_add_f32_e32 v167, v167, v190
	s_add_i32 s42, s31, 1
	s_movk_i32 s47, 7

.Lattn_tb3:
	s_waitcnt lgkmcnt(5)
	v_mfma_f32_32x32x16_bf16 v[48:63], v[216:219], v[144:147], v[48:63]
	ds_read_b128 v[216:219], v188 offset:8192
	s_add_i32 s2, s42, 4
	s_waitcnt lgkmcnt(5)
	v_mfma_f32_32x32x16_bf16 v[32:47], v[220:223], v[144:147], v[32:47]
	ds_read_b128 v[220:223], v188 offset:12288
	s_and_b32 s2, s2, 31
	s_waitcnt lgkmcnt(5)
	v_mfma_f32_32x32x16_bf16 v[16:31], v[224:227], v[144:147], v[16:31]
	ds_read_b128 v[224:227], v186 offset:0
	s_mul_i32 s2, s2, 0x44000
	s_waitcnt lgkmcnt(5)
	v_mfma_f32_32x32x16_bf16 v[0:15], v[228:231], v[144:147], v[0:15]
	ds_read_b128 v[228:231], v186 offset:4096
	s_add_u32 s48, s26, s2
	s_waitcnt lgkmcnt(5)
	v_mfma_f32_32x32x16_bf16 v[48:63], v[208:211], v[148:151], v[48:63]
	ds_read_b128 v[208:211], v186 offset:8192
	s_addc_u32 s49, s27, 0
	s_waitcnt lgkmcnt(5)
	v_mfma_f32_32x32x16_bf16 v[32:47], v[212:215], v[148:151], v[32:47]
	ds_read_b128 v[212:215], v186 offset:12288
	s_add_u32 s50, s48, 0x80
	s_waitcnt lgkmcnt(5)
	v_mfma_f32_32x32x16_bf16 v[16:31], v[216:219], v[148:151], v[16:31]
	ds_read_b128 v[216:219], v189 offset:0
	s_addc_u32 s51, s49, 0
	s_waitcnt lgkmcnt(5)
	v_mfma_f32_32x32x16_bf16 v[0:15], v[220:223], v[148:151], v[0:15]
	ds_read_b128 v[220:223], v189 offset:4096
	s_add_i32 s2, s42, 2
	s_waitcnt lgkmcnt(5)
	v_mfma_f32_32x32x16_bf16 v[48:63], v[224:227], v[152:155], v[48:63]
	ds_read_b128 v[224:227], v189 offset:8192
	s_and_b32 s2, s2, 31
	s_waitcnt lgkmcnt(5)
	v_mfma_f32_32x32x16_bf16 v[32:47], v[228:231], v[152:155], v[32:47]
	ds_read_b128 v[228:231], v189 offset:12288
	s_lshl_b32 s2, s2, 7
	s_waitcnt lgkmcnt(5)
	v_mfma_f32_32x32x16_bf16 v[16:31], v[208:211], v[152:155], v[16:31]
	ds_read_b128 v[208:211], v182 offset:32768
	s_add_u32 s52, s10, s2
	s_waitcnt lgkmcnt(5)
	v_mfma_f32_32x32x16_bf16 v[0:15], v[212:215], v[152:155], v[0:15]
	ds_read_b128 v[212:215], v182 offset:36864
	s_addc_u32 s53, s11, 0
	s_waitcnt lgkmcnt(5)
	v_mfma_f32_32x32x16_bf16 v[48:63], v[216:219], v[156:159], v[48:63]
	ds_read_b128 v[216:219], v183 offset:32768
	s_add_u32 s54, s52, 0x204000
	s_waitcnt lgkmcnt(5)
	v_mfma_f32_32x32x16_bf16 v[32:47], v[220:223], v[156:159], v[32:47]
	ds_read_b128 v[220:223], v183 offset:36864
	s_addc_u32 s55, s53, 0
	s_waitcnt lgkmcnt(5)
	v_mfma_f32_32x32x16_bf16 v[16:31], v[224:227], v[156:159], v[16:31]
	ds_read_b128 v[224:227], v184 offset:32768
	s_waitcnt lgkmcnt(5)
	v_mfma_f32_32x32x16_bf16 v[0:15], v[228:231], v[156:159], v[0:15]
	ds_read_b128 v[228:231], v184 offset:36864
	s_waitcnt lgkmcnt(5)
	v_mfma_f32_32x32x16_bf16 v[64:79], v[208:211], v[128:131], 0
	ds_read_b128 v[208:211], v185 offset:32768
	s_waitcnt lgkmcnt(5)
	v_mfma_f32_32x32x16_bf16 v[80:95], v[212:215], v[128:131], 0
	ds_read_b128 v[212:215], v185 offset:36864
	s_waitcnt lgkmcnt(5)
	v_mfma_f32_32x32x16_bf16 v[64:79], v[216:219], v[132:135], v[64:79]
	s_waitcnt lgkmcnt(4)
	v_mfma_f32_32x32x16_bf16 v[80:95], v[220:223], v[132:135], v[80:95]
	s_waitcnt lgkmcnt(3)
	v_mfma_f32_32x32x16_bf16 v[64:79], v[224:227], v[136:139], v[64:79]
	s_waitcnt lgkmcnt(2)
	v_mfma_f32_32x32x16_bf16 v[80:95], v[228:231], v[136:139], v[80:95]
	s_waitcnt lgkmcnt(1)
	v_mfma_f32_32x32x16_bf16 v[64:79], v[208:211], v[140:143], v[64:79]
	s_waitcnt lgkmcnt(0)
	v_mfma_f32_32x32x16_bf16 v[80:95], v[212:215], v[140:143], v[80:95]
	s_cmp_lg_u32 s14, 0
	s_cbranch_scc0 .Lattn_tb4
	s_waitcnt vmcnt(4)
	s_barrier
.Lattn_tb4:
	ds_read_b128 v[216:219], v187 offset:16384
	ds_read_b128 v[220:223], v187 offset:20480
	ds_read_b128 v[224:227], v187 offset:24576
	ds_read_b128 v[228:231], v187 offset:28672
	ds_read_b128 v[208:211], v188 offset:16384
	ds_read_b128 v[212:215], v188 offset:20480
	v_exp_f32_e32 v171, v96
	v_exp_f32_e32 v173, v97
	v_exp_f32_e32 v179, v98
	s_add_i32 m0, s5, 16384
	v_exp_f32_e32 v180, v99
	v_exp_f32_e32 v232, v100
	v_exp_f32_e32 v233, v101
	global_load_lds_dwordx4 v170, s[48:49]
	v_exp_f32_e32 v234, v102
	v_exp_f32_e32 v235, v103
	v_add_f32_e32 v190, v171, v173
	s_add_i32 m0, s5, 24576
	v_add_f32_e32 v191, v179, v180
	v_add_f32_e32 v190, v190, v232
	v_add_f32_e32 v191, v191, v233
	global_load_lds_dwordx4 v170, s[50:51]
	v_add_f32_e32 v190, v190, v234
	v_add_f32_e32 v191, v191, v235
	v_cvt_pk_bf16_f32 v144, v171, v173
	s_add_i32 m0, s5, 114688
	v_cvt_pk_bf16_f32 v145, v179, v180
	v_cvt_pk_bf16_f32 v146, v232, v233
	v_cvt_pk_bf16_f32 v147, v234, v235
	global_load_lds_dwordx4 v172, s[52:53]
	v_exp_f32_e32 v171, v104
	v_exp_f32_e32 v173, v105
	v_exp_f32_e32 v179, v106
	s_add_i32 m0, s5, 122880
	v_exp_f32_e32 v180, v107
	v_exp_f32_e32 v232, v108
	v_exp_f32_e32 v233, v109
	global_load_lds_dwordx4 v172, s[54:55]
	v_exp_f32_e32 v234, v110
	v_exp_f32_e32 v235, v111
	v_add_f32_e32 v190, v190, v171
	v_add_f32_e32 v191, v191, v173
	v_add_f32_e32 v190, v190, v179
	v_add_f32_e32 v191, v191, v180
	v_add_f32_e32 v190, v190, v232
	v_add_f32_e32 v191, v191, v233
	v_add_f32_e32 v190, v190, v234
	v_add_f32_e32 v191, v191, v235
	v_cvt_pk_bf16_f32 v148, v171, v173
	v_cvt_pk_bf16_f32 v149, v179, v180
	v_cvt_pk_bf16_f32 v150, v232, v233
	v_cvt_pk_bf16_f32 v151, v234, v235
	v_exp_f32_e32 v171, v112
	v_exp_f32_e32 v173, v113
	v_exp_f32_e32 v179, v114
	v_exp_f32_e32 v180, v115
	v_exp_f32_e32 v232, v116
	v_exp_f32_e32 v233, v117
	v_exp_f32_e32 v234, v118
	v_exp_f32_e32 v235, v119
	v_add_f32_e32 v190, v190, v171
	v_add_f32_e32 v191, v191, v173
	v_add_f32_e32 v190, v190, v179
	v_add_f32_e32 v191, v191, v180
	v_add_f32_e32 v190, v190, v232
	v_add_f32_e32 v191, v191, v233
	v_add_f32_e32 v190, v190, v234
	v_add_f32_e32 v191, v191, v235
	v_cvt_pk_bf16_f32 v152, v171, v173
	v_cvt_pk_bf16_f32 v153, v179, v180
	v_cvt_pk_bf16_f32 v154, v232, v233
	v_cvt_pk_bf16_f32 v155, v234, v235
	v_exp_f32_e32 v171, v120
	v_exp_f32_e32 v173, v121
	v_exp_f32_e32 v179, v122
	v_exp_f32_e32 v180, v123
	v_exp_f32_e32 v232, v124
	v_exp_f32_e32 v233, v125
	v_exp_f32_e32 v234, v126
	v_exp_f32_e32 v235, v127
	v_add_f32_e32 v190, v190, v171
	v_add_f32_e32 v191, v191, v173
	v_add_f32_e32 v190, v190, v179
	v_add_f32_e32 v191, v191, v180
	v_add_f32_e32 v190, v190, v232
	v_add_f32_e32 v191, v191, v233
	v_add_f32_e32 v190, v190, v234
	v_add_f32_e32 v191, v191, v235
	v_add_f32_e32 v190, v190, v191
	v_cmp_ngt_f32_e32 vcc, 0x71800000, v190
	v_cvt_pk_bf16_f32 v156, v171, v173
	v_cvt_pk_bf16_f32 v157, v179, v180
	v_cvt_pk_bf16_f32 v158, v232, v233
	v_cvt_pk_bf16_f32 v159, v234, v235
	s_nop 0
	s_cbranch_vccnz .Lattn_redo_L0
	v_add_f32_e32 v167, v167, v190
	s_cmp_lg_u32 s14, 0
	s_cbranch_scc1 .Lattn_tb5
	s_waitcnt vmcnt(4)
	s_barrier
.Lattn_tb5:
	s_waitcnt lgkmcnt(5)
	v_mfma_f32_32x32x16_bf16 v[48:63], v[216:219], v[144:147], v[48:63]
	ds_read_b128 v[216:219], v188 offset:24576
	s_add_i32 s2, s42, 5
	s_waitcnt lgkmcnt(5)
	v_mfma_f32_32x32x16_bf16 v[32:47], v[220:223], v[144:147], v[32:47]
	ds_read_b128 v[220:223], v188 offset:28672
	s_and_b32 s2, s2, 31
	s_waitcnt lgkmcnt(5)
	v_mfma_f32_32x32x16_bf16 v[16:31], v[224:227], v[144:147], v[16:31]
	ds_read_b128 v[224:227], v186 offset:16384
	s_mul_i32 s2, s2, 0x44000
	s_waitcnt lgkmcnt(5)
	v_mfma_f32_32x32x16_bf16 v[0:15], v[228:231], v[144:147], v[0:15]
	ds_read_b128 v[228:231], v186 offset:20480
	s_add_u32 s48, s26, s2
	s_waitcnt lgkmcnt(5)
	v_mfma_f32_32x32x16_bf16 v[48:63], v[208:211], v[148:151], v[48:63]
	ds_read_b128 v[208:211], v186 offset:24576
	s_addc_u32 s49, s27, 0
	s_waitcnt lgkmcnt(5)
	v_mfma_f32_32x32x16_bf16 v[32:47], v[212:215], v[148:151], v[32:47]
	ds_read_b128 v[212:215], v186 offset:28672
	s_add_u32 s50, s48, 0x80
	s_waitcnt lgkmcnt(5)
	v_mfma_f32_32x32x16_bf16 v[16:31], v[216:219], v[148:151], v[16:31]
	ds_read_b128 v[216:219], v189 offset:16384
	s_addc_u32 s51, s49, 0
	s_waitcnt lgkmcnt(5)
	v_mfma_f32_32x32x16_bf16 v[0:15], v[220:223], v[148:151], v[0:15]
	ds_read_b128 v[220:223], v189 offset:20480
	s_add_i32 s2, s42, 3
	s_waitcnt lgkmcnt(5)
	v_mfma_f32_32x32x16_bf16 v[48:63], v[224:227], v[152:155], v[48:63]
	ds_read_b128 v[224:227], v189 offset:24576
	s_and_b32 s2, s2, 31
	s_waitcnt lgkmcnt(5)
	v_mfma_f32_32x32x16_bf16 v[32:47], v[228:231], v[152:155], v[32:47]
	ds_read_b128 v[228:231], v189 offset:28672
	s_lshl_b32 s2, s2, 7
	s_waitcnt lgkmcnt(5)
	v_mfma_f32_32x32x16_bf16 v[16:31], v[208:211], v[152:155], v[16:31]
	ds_read_b128 v[208:211], v182 offset:49152
	s_add_u32 s52, s10, s2
	s_waitcnt lgkmcnt(5)
	v_mfma_f32_32x32x16_bf16 v[0:15], v[212:215], v[152:155], v[0:15]
	ds_read_b128 v[212:215], v182 offset:53248
	s_addc_u32 s53, s11, 0
	s_waitcnt lgkmcnt(5)
	v_mfma_f32_32x32x16_bf16 v[48:63], v[216:219], v[156:159], v[48:63]
	ds_read_b128 v[216:219], v183 offset:49152
	s_add_u32 s54, s52, 0x204000
	s_waitcnt lgkmcnt(5)
	v_mfma_f32_32x32x16_bf16 v[32:47], v[220:223], v[156:159], v[32:47]
	ds_read_b128 v[220:223], v183 offset:53248
	s_addc_u32 s55, s53, 0
	s_waitcnt lgkmcnt(5)
	v_mfma_f32_32x32x16_bf16 v[16:31], v[224:227], v[156:159], v[16:31]
	ds_read_b128 v[224:227], v184 offset:49152
	s_waitcnt lgkmcnt(5)
	v_mfma_f32_32x32x16_bf16 v[0:15], v[228:231], v[156:159], v[0:15]
	ds_read_b128 v[228:231], v184 offset:53248
	s_waitcnt lgkmcnt(5)
	v_mfma_f32_32x32x16_bf16 v[96:111], v[208:211], v[128:131], 0
	ds_read_b128 v[208:211], v185 offset:49152
	s_waitcnt lgkmcnt(5)
	v_mfma_f32_32x32x16_bf16 v[112:127], v[212:215], v[128:131], 0
	ds_read_b128 v[212:215], v185 offset:53248
	s_waitcnt lgkmcnt(5)
	v_mfma_f32_32x32x16_bf16 v[96:111], v[216:219], v[132:135], v[96:111]
	s_waitcnt lgkmcnt(4)
	v_mfma_f32_32x32x16_bf16 v[112:127], v[220:223], v[132:135], v[112:127]
	s_waitcnt lgkmcnt(3)
	v_mfma_f32_32x32x16_bf16 v[96:111], v[224:227], v[136:139], v[96:111]
	s_waitcnt lgkmcnt(2)
	v_mfma_f32_32x32x16_bf16 v[112:127], v[228:231], v[136:139], v[112:127]
	s_waitcnt lgkmcnt(1)
	v_mfma_f32_32x32x16_bf16 v[96:111], v[208:211], v[140:143], v[96:111]
	s_waitcnt lgkmcnt(0)
	v_mfma_f32_32x32x16_bf16 v[112:127], v[212:215], v[140:143], v[112:127]
	s_cmp_lg_u32 s14, 0
	s_cbranch_scc0 .Lattn_tb6
	s_waitcnt vmcnt(4)
	s_barrier
.Lattn_tb6:
	ds_read_b128 v[216:219], v187 offset:32768
	ds_read_b128 v[220:223], v187 offset:36864
	ds_read_b128 v[224:227], v187 offset:40960
	ds_read_b128 v[228:231], v187 offset:45056
	ds_read_b128 v[208:211], v188 offset:32768
	ds_read_b128 v[212:215], v188 offset:36864
	v_exp_f32_e32 v171, v64
	v_exp_f32_e32 v173, v65
	v_exp_f32_e32 v179, v66
	s_add_i32 m0, s5, 32768
	v_exp_f32_e32 v180, v67
	v_exp_f32_e32 v232, v68
	v_exp_f32_e32 v233, v69
	global_load_lds_dwordx4 v170, s[48:49]
	v_exp_f32_e32 v234, v70
	v_exp_f32_e32 v235, v71
	v_add_f32_e32 v190, v171, v173
	s_add_i32 m0, s5, 40960
	v_add_f32_e32 v191, v179, v180
	v_add_f32_e32 v190, v190, v232
	v_add_f32_e32 v191, v191, v233
	global_load_lds_dwordx4 v170, s[50:51]
	v_add_f32_e32 v190, v190, v234
	v_add_f32_e32 v191, v191, v235
	v_cvt_pk_bf16_f32 v144, v171, v173
	s_add_i32 m0, s5, 65536
	v_cvt_pk_bf16_f32 v145, v179, v180
	v_cvt_pk_bf16_f32 v146, v232, v233
	v_cvt_pk_bf16_f32 v147, v234, v235
	global_load_lds_dwordx4 v172, s[52:53]
	v_exp_f32_e32 v171, v72
	v_exp_f32_e32 v173, v73
	v_exp_f32_e32 v179, v74
	s_add_i32 m0, s5, 73728
	v_exp_f32_e32 v180, v75
	v_exp_f32_e32 v232, v76
	v_exp_f32_e32 v233, v77
	global_load_lds_dwordx4 v172, s[54:55]
	v_exp_f32_e32 v234, v78
	v_exp_f32_e32 v235, v79
	v_add_f32_e32 v190, v190, v171
	v_add_f32_e32 v191, v191, v173
	v_add_f32_e32 v190, v190, v179
	v_add_f32_e32 v191, v191, v180
	v_add_f32_e32 v190, v190, v232
	v_add_f32_e32 v191, v191, v233
	v_add_f32_e32 v190, v190, v234
	v_add_f32_e32 v191, v191, v235
	v_cvt_pk_bf16_f32 v148, v171, v173
	v_cvt_pk_bf16_f32 v149, v179, v180
	v_cvt_pk_bf16_f32 v150, v232, v233
	v_cvt_pk_bf16_f32 v151, v234, v235
	v_exp_f32_e32 v171, v80
	v_exp_f32_e32 v173, v81
	v_exp_f32_e32 v179, v82
	v_exp_f32_e32 v180, v83
	v_exp_f32_e32 v232, v84
	v_exp_f32_e32 v233, v85
	v_exp_f32_e32 v234, v86
	v_exp_f32_e32 v235, v87
	v_add_f32_e32 v190, v190, v171
	v_add_f32_e32 v191, v191, v173
	v_add_f32_e32 v190, v190, v179
	v_add_f32_e32 v191, v191, v180
	v_add_f32_e32 v190, v190, v232
	v_add_f32_e32 v191, v191, v233
	v_add_f32_e32 v190, v190, v234
	v_add_f32_e32 v191, v191, v235
	v_cvt_pk_bf16_f32 v152, v171, v173
	v_cvt_pk_bf16_f32 v153, v179, v180
	v_cvt_pk_bf16_f32 v154, v232, v233
	v_cvt_pk_bf16_f32 v155, v234, v235
	v_exp_f32_e32 v171, v88
	v_exp_f32_e32 v173, v89
	v_exp_f32_e32 v179, v90
	v_exp_f32_e32 v180, v91
	v_exp_f32_e32 v232, v92
	v_exp_f32_e32 v233, v93
	v_exp_f32_e32 v234, v94
	v_exp_f32_e32 v235, v95
	v_add_f32_e32 v190, v190, v171
	v_add_f32_e32 v191, v191, v173
	v_add_f32_e32 v190, v190, v179
	v_add_f32_e32 v191, v191, v180
	v_add_f32_e32 v190, v190, v232
	v_add_f32_e32 v191, v191, v233
	v_add_f32_e32 v190, v190, v234
	v_add_f32_e32 v191, v191, v235
	v_add_f32_e32 v190, v190, v191
	v_cmp_ngt_f32_e32 vcc, 0x71800000, v190
	v_cvt_pk_bf16_f32 v156, v171, v173
	v_cvt_pk_bf16_f32 v157, v179, v180
	v_cvt_pk_bf16_f32 v158, v232, v233
	v_cvt_pk_bf16_f32 v159, v234, v235
	s_nop 0
	s_cbranch_vccnz .Lattn_redo_L1
	v_add_f32_e32 v167, v167, v190
	s_cmp_lg_u32 s14, 0
	s_cbranch_scc1 .Lattn_tb7
	s_waitcnt vmcnt(4)
	s_barrier
.Lattn_tb7:
	s_waitcnt lgkmcnt(5)
	v_mfma_f32_32x32x16_bf16 v[48:63], v[216:219], v[144:147], v[48:63]
	ds_read_b128 v[216:219], v188 offset:40960
	s_add_i32 s2, s42, 6
	s_waitcnt lgkmcnt(5)
	v_mfma_f32_32x32x16_bf16 v[32:47], v[220:223], v[144:147], v[32:47]
	ds_read_b128 v[220:223], v188 offset:45056
	s_and_b32 s2, s2, 31
	s_waitcnt lgkmcnt(5)
	v_mfma_f32_32x32x16_bf16 v[16:31], v[224:227], v[144:147], v[16:31]
	ds_read_b128 v[224:227], v186 offset:32768
	s_mul_i32 s2, s2, 0x44000
	s_waitcnt lgkmcnt(5)
	v_mfma_f32_32x32x16_bf16 v[0:15], v[228:231], v[144:147], v[0:15]
	ds_read_b128 v[228:231], v186 offset:36864
	s_add_u32 s48, s26, s2
	s_waitcnt lgkmcnt(5)
	v_mfma_f32_32x32x16_bf16 v[48:63], v[208:211], v[148:151], v[48:63]
	ds_read_b128 v[208:211], v186 offset:40960
	s_addc_u32 s49, s27, 0
	s_waitcnt lgkmcnt(5)
	v_mfma_f32_32x32x16_bf16 v[32:47], v[212:215], v[148:151], v[32:47]
	ds_read_b128 v[212:215], v186 offset:45056
	s_add_u32 s50, s48, 0x80
	s_waitcnt lgkmcnt(5)
	v_mfma_f32_32x32x16_bf16 v[16:31], v[216:219], v[148:151], v[16:31]
	ds_read_b128 v[216:219], v189 offset:32768
	s_addc_u32 s51, s49, 0
	s_waitcnt lgkmcnt(5)
	v_mfma_f32_32x32x16_bf16 v[0:15], v[220:223], v[148:151], v[0:15]
	ds_read_b128 v[220:223], v189 offset:36864
	s_add_i32 s2, s42, 4
	s_waitcnt lgkmcnt(5)
	v_mfma_f32_32x32x16_bf16 v[48:63], v[224:227], v[152:155], v[48:63]
	ds_read_b128 v[224:227], v189 offset:40960
	s_and_b32 s2, s2, 31
	s_waitcnt lgkmcnt(5)
	v_mfma_f32_32x32x16_bf16 v[32:47], v[228:231], v[152:155], v[32:47]
	ds_read_b128 v[228:231], v189 offset:45056
	s_lshl_b32 s2, s2, 7
	s_waitcnt lgkmcnt(5)
	v_mfma_f32_32x32x16_bf16 v[16:31], v[208:211], v[152:155], v[16:31]
	ds_read_b128 v[208:211], v182 offset:0
	s_add_u32 s52, s10, s2
	s_waitcnt lgkmcnt(5)
	v_mfma_f32_32x32x16_bf16 v[0:15], v[212:215], v[152:155], v[0:15]
	ds_read_b128 v[212:215], v182 offset:4096
	s_addc_u32 s53, s11, 0
	s_waitcnt lgkmcnt(5)
	v_mfma_f32_32x32x16_bf16 v[48:63], v[216:219], v[156:159], v[48:63]
	ds_read_b128 v[216:219], v183 offset:0
	s_add_u32 s54, s52, 0x204000
	s_waitcnt lgkmcnt(5)
	v_mfma_f32_32x32x16_bf16 v[32:47], v[220:223], v[156:159], v[32:47]
	ds_read_b128 v[220:223], v183 offset:4096
	s_addc_u32 s55, s53, 0
	s_waitcnt lgkmcnt(5)
	v_mfma_f32_32x32x16_bf16 v[16:31], v[224:227], v[156:159], v[16:31]
	ds_read_b128 v[224:227], v184 offset:0
	s_waitcnt lgkmcnt(5)
	v_mfma_f32_32x32x16_bf16 v[0:15], v[228:231], v[156:159], v[0:15]
	ds_read_b128 v[228:231], v184 offset:4096
	s_waitcnt lgkmcnt(5)
	v_mfma_f32_32x32x16_bf16 v[64:79], v[208:211], v[128:131], 0
	ds_read_b128 v[208:211], v185 offset:0
	s_waitcnt lgkmcnt(5)
	v_mfma_f32_32x32x16_bf16 v[80:95], v[212:215], v[128:131], 0
	ds_read_b128 v[212:215], v185 offset:4096
	s_waitcnt lgkmcnt(5)
	v_mfma_f32_32x32x16_bf16 v[64:79], v[216:219], v[132:135], v[64:79]
	s_waitcnt lgkmcnt(4)
	v_mfma_f32_32x32x16_bf16 v[80:95], v[220:223], v[132:135], v[80:95]
	s_waitcnt lgkmcnt(3)
	v_mfma_f32_32x32x16_bf16 v[64:79], v[224:227], v[136:139], v[64:79]
	s_waitcnt lgkmcnt(2)
	v_mfma_f32_32x32x16_bf16 v[80:95], v[228:231], v[136:139], v[80:95]
	s_waitcnt lgkmcnt(1)
	v_mfma_f32_32x32x16_bf16 v[64:79], v[208:211], v[140:143], v[64:79]
	s_waitcnt lgkmcnt(0)
	v_mfma_f32_32x32x16_bf16 v[80:95], v[212:215], v[140:143], v[80:95]
	s_cmp_lg_u32 s14, 0
	s_cbranch_scc0 .Lattn_tb8
	s_waitcnt vmcnt(4)
	s_barrier
.Lattn_tb8:
	ds_read_b128 v[216:219], v187 offset:49152
	ds_read_b128 v[220:223], v187 offset:53248
	ds_read_b128 v[224:227], v187 offset:57344
	ds_read_b128 v[228:231], v187 offset:61440
	ds_read_b128 v[208:211], v188 offset:49152
	ds_read_b128 v[212:215], v188 offset:53248
	v_exp_f32_e32 v171, v96
	v_exp_f32_e32 v173, v97
	v_exp_f32_e32 v179, v98
	s_add_i32 m0, s5, 49152
	v_exp_f32_e32 v180, v99
	v_exp_f32_e32 v232, v100
	v_exp_f32_e32 v233, v101
	global_load_lds_dwordx4 v170, s[48:49]
	v_exp_f32_e32 v234, v102
	v_exp_f32_e32 v235, v103
	v_add_f32_e32 v190, v171, v173
	s_add_i32 m0, s5, 57344
	v_add_f32_e32 v191, v179, v180
	v_add_f32_e32 v190, v190, v232
	v_add_f32_e32 v191, v191, v233
	global_load_lds_dwordx4 v170, s[50:51]
	v_add_f32_e32 v190, v190, v234
	v_add_f32_e32 v191, v191, v235
	v_cvt_pk_bf16_f32 v144, v171, v173
	s_add_i32 m0, s5, 81920
	v_cvt_pk_bf16_f32 v145, v179, v180
	v_cvt_pk_bf16_f32 v146, v232, v233
	v_cvt_pk_bf16_f32 v147, v234, v235
	global_load_lds_dwordx4 v172, s[52:53]
	v_exp_f32_e32 v171, v104
	v_exp_f32_e32 v173, v105
	v_exp_f32_e32 v179, v106
	s_add_i32 m0, s5, 90112
	v_exp_f32_e32 v180, v107
	v_exp_f32_e32 v232, v108
	v_exp_f32_e32 v233, v109
	global_load_lds_dwordx4 v172, s[54:55]
	v_exp_f32_e32 v234, v110
	v_exp_f32_e32 v235, v111
	v_add_f32_e32 v190, v190, v171
	v_add_f32_e32 v191, v191, v173
	v_add_f32_e32 v190, v190, v179
	v_add_f32_e32 v191, v191, v180
	v_add_f32_e32 v190, v190, v232
	v_add_f32_e32 v191, v191, v233
	v_add_f32_e32 v190, v190, v234
	v_add_f32_e32 v191, v191, v235
	v_cvt_pk_bf16_f32 v148, v171, v173
	v_cvt_pk_bf16_f32 v149, v179, v180
	v_cvt_pk_bf16_f32 v150, v232, v233
	v_cvt_pk_bf16_f32 v151, v234, v235
	v_exp_f32_e32 v171, v112
	v_exp_f32_e32 v173, v113
	v_exp_f32_e32 v179, v114
	v_exp_f32_e32 v180, v115
	v_exp_f32_e32 v232, v116
	v_exp_f32_e32 v233, v117
	v_exp_f32_e32 v234, v118
	v_exp_f32_e32 v235, v119
	v_add_f32_e32 v190, v190, v171
	v_add_f32_e32 v191, v191, v173
	v_add_f32_e32 v190, v190, v179
	v_add_f32_e32 v191, v191, v180
	v_add_f32_e32 v190, v190, v232
	v_add_f32_e32 v191, v191, v233
	v_add_f32_e32 v190, v190, v234
	v_add_f32_e32 v191, v191, v235
	v_cvt_pk_bf16_f32 v152, v171, v173
	v_cvt_pk_bf16_f32 v153, v179, v180
	v_cvt_pk_bf16_f32 v154, v232, v233
	v_cvt_pk_bf16_f32 v155, v234, v235
	v_exp_f32_e32 v171, v120
	v_exp_f32_e32 v173, v121
	v_exp_f32_e32 v179, v122
	v_exp_f32_e32 v180, v123
	v_exp_f32_e32 v232, v124
	v_exp_f32_e32 v233, v125
	v_exp_f32_e32 v234, v126
	v_exp_f32_e32 v235, v127
	v_add_f32_e32 v190, v190, v171
	v_add_f32_e32 v191, v191, v173
	v_add_f32_e32 v190, v190, v179
	v_add_f32_e32 v191, v191, v180
	v_add_f32_e32 v190, v190, v232
	v_add_f32_e32 v191, v191, v233
	v_add_f32_e32 v190, v190, v234
	v_add_f32_e32 v191, v191, v235
	v_add_f32_e32 v190, v190, v191
	v_cmp_ngt_f32_e32 vcc, 0x71800000, v190
	v_cvt_pk_bf16_f32 v156, v171, v173
	v_cvt_pk_bf16_f32 v157, v179, v180
	v_cvt_pk_bf16_f32 v158, v232, v233
	v_cvt_pk_bf16_f32 v159, v234, v235
	s_nop 0
	s_cbranch_vccnz .Lattn_redo_L2
	v_add_f32_e32 v167, v167, v190
	s_cmp_lg_u32 s14, 0
	s_cbranch_scc1 .Lattn_tb9
	s_waitcnt vmcnt(4)
	s_barrier
.Lattn_tb9:
	s_waitcnt lgkmcnt(5)
	v_mfma_f32_32x32x16_bf16 v[48:63], v[216:219], v[144:147], v[48:63]
	ds_read_b128 v[216:219], v188 offset:57344
	s_add_i32 s2, s42, 7
	s_waitcnt lgkmcnt(5)
	v_mfma_f32_32x32x16_bf16 v[32:47], v[220:223], v[144:147], v[32:47]
	ds_read_b128 v[220:223], v188 offset:61440
	s_and_b32 s2, s2, 31
	s_waitcnt lgkmcnt(5)
	v_mfma_f32_32x32x16_bf16 v[16:31], v[224:227], v[144:147], v[16:31]
	ds_read_b128 v[224:227], v186 offset:49152
	s_mul_i32 s2, s2, 0x44000
	s_waitcnt lgkmcnt(5)
	v_mfma_f32_32x32x16_bf16 v[0:15], v[228:231], v[144:147], v[0:15]
	ds_read_b128 v[228:231], v186 offset:53248
	s_add_u32 s48, s26, s2
	s_waitcnt lgkmcnt(5)
	v_mfma_f32_32x32x16_bf16 v[48:63], v[208:211], v[148:151], v[48:63]
	ds_read_b128 v[208:211], v186 offset:57344
	s_addc_u32 s49, s27, 0
	s_waitcnt lgkmcnt(5)
	v_mfma_f32_32x32x16_bf16 v[32:47], v[212:215], v[148:151], v[32:47]
	ds_read_b128 v[212:215], v186 offset:61440
	s_add_u32 s50, s48, 0x80
	s_waitcnt lgkmcnt(5)
	v_mfma_f32_32x32x16_bf16 v[16:31], v[216:219], v[148:151], v[16:31]
	ds_read_b128 v[216:219], v189 offset:49152
	s_addc_u32 s51, s49, 0
	s_waitcnt lgkmcnt(5)
	v_mfma_f32_32x32x16_bf16 v[0:15], v[220:223], v[148:151], v[0:15]
	ds_read_b128 v[220:223], v189 offset:53248
	s_add_i32 s2, s42, 5
	s_waitcnt lgkmcnt(5)
	v_mfma_f32_32x32x16_bf16 v[48:63], v[224:227], v[152:155], v[48:63]
	ds_read_b128 v[224:227], v189 offset:57344
	s_and_b32 s2, s2, 31
	s_waitcnt lgkmcnt(5)
	v_mfma_f32_32x32x16_bf16 v[32:47], v[228:231], v[152:155], v[32:47]
	ds_read_b128 v[228:231], v189 offset:61440
	s_lshl_b32 s2, s2, 7
	s_waitcnt lgkmcnt(5)
	v_mfma_f32_32x32x16_bf16 v[16:31], v[208:211], v[152:155], v[16:31]
	ds_read_b128 v[208:211], v182 offset:16384
	s_add_u32 s52, s10, s2
	s_waitcnt lgkmcnt(5)
	v_mfma_f32_32x32x16_bf16 v[0:15], v[212:215], v[152:155], v[0:15]
	ds_read_b128 v[212:215], v182 offset:20480
	s_addc_u32 s53, s11, 0
	s_waitcnt lgkmcnt(5)
	v_mfma_f32_32x32x16_bf16 v[48:63], v[216:219], v[156:159], v[48:63]
	ds_read_b128 v[216:219], v183 offset:16384
	s_add_u32 s54, s52, 0x204000
	s_waitcnt lgkmcnt(5)
	v_mfma_f32_32x32x16_bf16 v[32:47], v[220:223], v[156:159], v[32:47]
	ds_read_b128 v[220:223], v183 offset:20480
	s_addc_u32 s55, s53, 0
	s_waitcnt lgkmcnt(5)
	v_mfma_f32_32x32x16_bf16 v[16:31], v[224:227], v[156:159], v[16:31]
	ds_read_b128 v[224:227], v184 offset:16384
	s_waitcnt lgkmcnt(5)
	v_mfma_f32_32x32x16_bf16 v[0:15], v[228:231], v[156:159], v[0:15]
	ds_read_b128 v[228:231], v184 offset:20480
	s_waitcnt lgkmcnt(5)
	v_mfma_f32_32x32x16_bf16 v[96:111], v[208:211], v[128:131], 0
	ds_read_b128 v[208:211], v185 offset:16384
	s_waitcnt lgkmcnt(5)
	v_mfma_f32_32x32x16_bf16 v[112:127], v[212:215], v[128:131], 0
	ds_read_b128 v[212:215], v185 offset:20480
	s_waitcnt lgkmcnt(5)
	v_mfma_f32_32x32x16_bf16 v[96:111], v[216:219], v[132:135], v[96:111]
	s_waitcnt lgkmcnt(4)
	v_mfma_f32_32x32x16_bf16 v[112:127], v[220:223], v[132:135], v[112:127]
	s_waitcnt lgkmcnt(3)
	v_mfma_f32_32x32x16_bf16 v[96:111], v[224:227], v[136:139], v[96:111]
	s_waitcnt lgkmcnt(2)
	v_mfma_f32_32x32x16_bf16 v[112:127], v[228:231], v[136:139], v[112:127]
	s_waitcnt lgkmcnt(1)
	v_mfma_f32_32x32x16_bf16 v[96:111], v[208:211], v[140:143], v[96:111]
	s_waitcnt lgkmcnt(0)
	v_mfma_f32_32x32x16_bf16 v[112:127], v[212:215], v[140:143], v[112:127]
	s_cmp_lg_u32 s14, 0
	s_cbranch_scc0 .Lattn_tb10
	s_waitcnt vmcnt(4)
	s_barrier
.Lattn_tb10:
	ds_read_b128 v[216:219], v187 offset:0
	ds_read_b128 v[220:223], v187 offset:4096
	ds_read_b128 v[224:227], v187 offset:8192
	ds_read_b128 v[228:231], v187 offset:12288
	ds_read_b128 v[208:211], v188 offset:0
	ds_read_b128 v[212:215], v188 offset:4096
	v_exp_f32_e32 v171, v64
	v_exp_f32_e32 v173, v65
	v_exp_f32_e32 v179, v66
	s_add_i32 m0, s5, 0
	v_exp_f32_e32 v180, v67
	v_exp_f32_e32 v232, v68
	v_exp_f32_e32 v233, v69
	global_load_lds_dwordx4 v170, s[48:49]
	v_exp_f32_e32 v234, v70
	v_exp_f32_e32 v235, v71
	v_add_f32_e32 v190, v171, v173
	s_add_i32 m0, s5, 8192
	v_add_f32_e32 v191, v179, v180
	v_add_f32_e32 v190, v190, v232
	v_add_f32_e32 v191, v191, v233
	global_load_lds_dwordx4 v170, s[50:51]
	v_add_f32_e32 v190, v190, v234
	v_add_f32_e32 v191, v191, v235
	v_cvt_pk_bf16_f32 v144, v171, v173
	s_add_i32 m0, s5, 98304
	v_cvt_pk_bf16_f32 v145, v179, v180
	v_cvt_pk_bf16_f32 v146, v232, v233
	v_cvt_pk_bf16_f32 v147, v234, v235
	global_load_lds_dwordx4 v172, s[52:53]
	v_exp_f32_e32 v171, v72
	v_exp_f32_e32 v173, v73
	v_exp_f32_e32 v179, v74
	s_add_i32 m0, s5, 106496
	v_exp_f32_e32 v180, v75
	v_exp_f32_e32 v232, v76
	v_exp_f32_e32 v233, v77
	global_load_lds_dwordx4 v172, s[54:55]
	v_exp_f32_e32 v234, v78
	v_exp_f32_e32 v235, v79
	v_add_f32_e32 v190, v190, v171
	v_add_f32_e32 v191, v191, v173
	v_add_f32_e32 v190, v190, v179
	v_add_f32_e32 v191, v191, v180
	v_add_f32_e32 v190, v190, v232
	v_add_f32_e32 v191, v191, v233
	v_add_f32_e32 v190, v190, v234
	v_add_f32_e32 v191, v191, v235
	v_cvt_pk_bf16_f32 v148, v171, v173
	v_cvt_pk_bf16_f32 v149, v179, v180
	v_cvt_pk_bf16_f32 v150, v232, v233
	v_cvt_pk_bf16_f32 v151, v234, v235
	v_exp_f32_e32 v171, v80
	v_exp_f32_e32 v173, v81
	v_exp_f32_e32 v179, v82
	v_exp_f32_e32 v180, v83
	v_exp_f32_e32 v232, v84
	v_exp_f32_e32 v233, v85
	v_exp_f32_e32 v234, v86
	v_exp_f32_e32 v235, v87
	v_add_f32_e32 v190, v190, v171
	v_add_f32_e32 v191, v191, v173
	v_add_f32_e32 v190, v190, v179
	v_add_f32_e32 v191, v191, v180
	v_add_f32_e32 v190, v190, v232
	v_add_f32_e32 v191, v191, v233
	v_add_f32_e32 v190, v190, v234
	v_add_f32_e32 v191, v191, v235
	v_cvt_pk_bf16_f32 v152, v171, v173
	v_cvt_pk_bf16_f32 v153, v179, v180
	v_cvt_pk_bf16_f32 v154, v232, v233
	v_cvt_pk_bf16_f32 v155, v234, v235
	v_exp_f32_e32 v171, v88
	v_exp_f32_e32 v173, v89
	v_exp_f32_e32 v179, v90
	v_exp_f32_e32 v180, v91
	v_exp_f32_e32 v232, v92
	v_exp_f32_e32 v233, v93
	v_exp_f32_e32 v234, v94
	v_exp_f32_e32 v235, v95
	v_add_f32_e32 v190, v190, v171
	v_add_f32_e32 v191, v191, v173
	v_add_f32_e32 v190, v190, v179
	v_add_f32_e32 v191, v191, v180
	v_add_f32_e32 v190, v190, v232
	v_add_f32_e32 v191, v191, v233
	v_add_f32_e32 v190, v190, v234
	v_add_f32_e32 v191, v191, v235
	v_add_f32_e32 v190, v190, v191
	v_cmp_ngt_f32_e32 vcc, 0x71800000, v190
	v_cvt_pk_bf16_f32 v156, v171, v173
	v_cvt_pk_bf16_f32 v157, v179, v180
	v_cvt_pk_bf16_f32 v158, v232, v233
	v_cvt_pk_bf16_f32 v159, v234, v235
	s_nop 0
	s_cbranch_vccnz .Lattn_redo_L3
	v_add_f32_e32 v167, v167, v190
	s_add_i32 s42, s42, 4
	s_add_i32 s47, s47, -1
	s_cmp_lg_u32 s47, 0
	s_cbranch_scc1 .Lattn_loop_f
	s_cmp_lg_u32 s14, 0
	s_cbranch_scc1 .Lattn_tb11
	s_waitcnt vmcnt(4)
	s_barrier
.Lattn_tb11:
	s_waitcnt lgkmcnt(5)
	v_mfma_f32_32x32x16_bf16 v[48:63], v[216:219], v[144:147], v[48:63]
	ds_read_b128 v[216:219], v188 offset:8192
	s_add_i32 s2, s42, 2
	s_waitcnt lgkmcnt(5)
	v_mfma_f32_32x32x16_bf16 v[32:47], v[220:223], v[144:147], v[32:47]
	ds_read_b128 v[220:223], v188 offset:12288
	s_and_b32 s2, s2, 31
	s_waitcnt lgkmcnt(5)
	v_mfma_f32_32x32x16_bf16 v[16:31], v[224:227], v[144:147], v[16:31]
	ds_read_b128 v[224:227], v186 offset:0
	s_lshl_b32 s2, s2, 7
	s_waitcnt lgkmcnt(5)
	v_mfma_f32_32x32x16_bf16 v[0:15], v[228:231], v[144:147], v[0:15]
	ds_read_b128 v[228:231], v186 offset:4096
	s_add_u32 s52, s10, s2
	s_waitcnt lgkmcnt(5)
	v_mfma_f32_32x32x16_bf16 v[48:63], v[208:211], v[148:151], v[48:63]
	ds_read_b128 v[208:211], v186 offset:8192
	s_addc_u32 s53, s11, 0
	s_waitcnt lgkmcnt(5)
	v_mfma_f32_32x32x16_bf16 v[32:47], v[212:215], v[148:151], v[32:47]
	ds_read_b128 v[212:215], v186 offset:12288
	s_add_u32 s54, s52, 0x204000
	s_waitcnt lgkmcnt(5)
	v_mfma_f32_32x32x16_bf16 v[16:31], v[216:219], v[148:151], v[16:31]
	ds_read_b128 v[216:219], v189 offset:0
	s_addc_u32 s55, s53, 0
	s_waitcnt lgkmcnt(5)
	v_mfma_f32_32x32x16_bf16 v[0:15], v[220:223], v[148:151], v[0:15]
	ds_read_b128 v[220:223], v189 offset:4096
	s_waitcnt lgkmcnt(5)
	v_mfma_f32_32x32x16_bf16 v[48:63], v[224:227], v[152:155], v[48:63]
	ds_read_b128 v[224:227], v189 offset:8192
	s_waitcnt lgkmcnt(5)
	v_mfma_f32_32x32x16_bf16 v[32:47], v[228:231], v[152:155], v[32:47]
	ds_read_b128 v[228:231], v189 offset:12288
	s_waitcnt lgkmcnt(5)
	v_mfma_f32_32x32x16_bf16 v[16:31], v[208:211], v[152:155], v[16:31]
	ds_read_b128 v[208:211], v182 offset:32768
	s_waitcnt lgkmcnt(5)
	v_mfma_f32_32x32x16_bf16 v[0:15], v[212:215], v[152:155], v[0:15]
	ds_read_b128 v[212:215], v182 offset:36864
	s_waitcnt lgkmcnt(5)
	v_mfma_f32_32x32x16_bf16 v[48:63], v[216:219], v[156:159], v[48:63]
	ds_read_b128 v[216:219], v183 offset:32768
	s_waitcnt lgkmcnt(5)
	v_mfma_f32_32x32x16_bf16 v[32:47], v[220:223], v[156:159], v[32:47]
	ds_read_b128 v[220:223], v183 offset:36864
	s_waitcnt lgkmcnt(5)
	v_mfma_f32_32x32x16_bf16 v[16:31], v[224:227], v[156:159], v[16:31]
	ds_read_b128 v[224:227], v184 offset:32768
	s_waitcnt lgkmcnt(5)
	v_mfma_f32_32x32x16_bf16 v[0:15], v[228:231], v[156:159], v[0:15]
	ds_read_b128 v[228:231], v184 offset:36864
	s_waitcnt lgkmcnt(5)
	v_mfma_f32_32x32x16_bf16 v[64:79], v[208:211], v[128:131], 0
	ds_read_b128 v[208:211], v185 offset:32768
	s_waitcnt lgkmcnt(5)
	v_mfma_f32_32x32x16_bf16 v[80:95], v[212:215], v[128:131], 0
	ds_read_b128 v[212:215], v185 offset:36864
	s_waitcnt lgkmcnt(5)
	v_mfma_f32_32x32x16_bf16 v[64:79], v[216:219], v[132:135], v[64:79]
	s_waitcnt lgkmcnt(4)
	v_mfma_f32_32x32x16_bf16 v[80:95], v[220:223], v[132:135], v[80:95]
	s_waitcnt lgkmcnt(3)
	v_mfma_f32_32x32x16_bf16 v[64:79], v[224:227], v[136:139], v[64:79]
	s_waitcnt lgkmcnt(2)
	v_mfma_f32_32x32x16_bf16 v[80:95], v[228:231], v[136:139], v[80:95]
	s_waitcnt lgkmcnt(1)
	v_mfma_f32_32x32x16_bf16 v[64:79], v[208:211], v[140:143], v[64:79]
	s_waitcnt lgkmcnt(0)
	v_mfma_f32_32x32x16_bf16 v[80:95], v[212:215], v[140:143], v[80:95]
	s_cmp_lg_u32 s14, 0
	s_cbranch_scc0 .Lattn_tb12
	s_waitcnt vmcnt(4)
	s_barrier
.Lattn_tb12:
	ds_read_b128 v[216:219], v187 offset:16384
	ds_read_b128 v[220:223], v187 offset:20480
	ds_read_b128 v[224:227], v187 offset:24576
	ds_read_b128 v[228:231], v187 offset:28672
	ds_read_b128 v[208:211], v188 offset:16384
	ds_read_b128 v[212:215], v188 offset:20480
	v_exp_f32_e32 v171, v96
	v_exp_f32_e32 v173, v97
	v_exp_f32_e32 v179, v98
	s_add_i32 m0, s5, 114688
	v_exp_f32_e32 v180, v99
	v_exp_f32_e32 v232, v100
	v_exp_f32_e32 v233, v101
	global_load_lds_dwordx4 v172, s[52:53]
	v_exp_f32_e32 v234, v102
	v_exp_f32_e32 v235, v103
	v_add_f32_e32 v190, v171, v173
	s_add_i32 m0, s5, 122880
	v_add_f32_e32 v191, v179, v180
	v_add_f32_e32 v190, v190, v232
	v_add_f32_e32 v191, v191, v233
	global_load_lds_dwordx4 v172, s[54:55]
	v_add_f32_e32 v190, v190, v234
	v_add_f32_e32 v191, v191, v235
	v_cvt_pk_bf16_f32 v144, v171, v173
	v_cvt_pk_bf16_f32 v145, v179, v180
	v_cvt_pk_bf16_f32 v146, v232, v233
	v_cvt_pk_bf16_f32 v147, v234, v235
	v_exp_f32_e32 v171, v104
	v_exp_f32_e32 v173, v105
	v_exp_f32_e32 v179, v106
	v_exp_f32_e32 v180, v107
	v_exp_f32_e32 v232, v108
	v_exp_f32_e32 v233, v109
	v_exp_f32_e32 v234, v110
	v_exp_f32_e32 v235, v111
	v_add_f32_e32 v190, v190, v171
	v_add_f32_e32 v191, v191, v173
	v_add_f32_e32 v190, v190, v179
	v_add_f32_e32 v191, v191, v180
	v_add_f32_e32 v190, v190, v232
	v_add_f32_e32 v191, v191, v233
	v_add_f32_e32 v190, v190, v234
	v_add_f32_e32 v191, v191, v235
	v_cvt_pk_bf16_f32 v148, v171, v173
	v_cvt_pk_bf16_f32 v149, v179, v180
	v_cvt_pk_bf16_f32 v150, v232, v233
	v_cvt_pk_bf16_f32 v151, v234, v235
	v_exp_f32_e32 v171, v112
	v_exp_f32_e32 v173, v113
	v_exp_f32_e32 v179, v114
	v_exp_f32_e32 v180, v115
	v_exp_f32_e32 v232, v116
	v_exp_f32_e32 v233, v117
	v_exp_f32_e32 v234, v118
	v_exp_f32_e32 v235, v119
	v_add_f32_e32 v190, v190, v171
	v_add_f32_e32 v191, v191, v173
	v_add_f32_e32 v190, v190, v179
	v_add_f32_e32 v191, v191, v180
	v_add_f32_e32 v190, v190, v232
	v_add_f32_e32 v191, v191, v233
	v_add_f32_e32 v190, v190, v234
	v_add_f32_e32 v191, v191, v235
	v_cvt_pk_bf16_f32 v152, v171, v173
	v_cvt_pk_bf16_f32 v153, v179, v180
	v_cvt_pk_bf16_f32 v154, v232, v233
	v_cvt_pk_bf16_f32 v155, v234, v235
	v_exp_f32_e32 v171, v120
	v_exp_f32_e32 v173, v121
	v_exp_f32_e32 v179, v122
	v_exp_f32_e32 v180, v123
	v_exp_f32_e32 v232, v124
	v_exp_f32_e32 v233, v125
	v_exp_f32_e32 v234, v126
	v_exp_f32_e32 v235, v127
	v_add_f32_e32 v190, v190, v171
	v_add_f32_e32 v191, v191, v173
	v_add_f32_e32 v190, v190, v179
	v_add_f32_e32 v191, v191, v180
	v_add_f32_e32 v190, v190, v232
	v_add_f32_e32 v191, v191, v233
	v_add_f32_e32 v190, v190, v234
	v_add_f32_e32 v191, v191, v235
	v_add_f32_e32 v190, v190, v191
	v_cmp_ngt_f32_e32 vcc, 0x71800000, v190
	v_cvt_pk_bf16_f32 v156, v171, v173
	v_cvt_pk_bf16_f32 v157, v179, v180
	v_cvt_pk_bf16_f32 v158, v232, v233
	v_cvt_pk_bf16_f32 v159, v234, v235
	s_nop 0
	s_cbranch_vccnz .Lattn_redo_T29
	v_add_f32_e32 v167, v167, v190
	s_cmp_lg_u32 s14, 0
	s_cbranch_scc1 .Lattn_tb13
	s_waitcnt vmcnt(2)
	s_barrier

.Lattn_pfvt_f:
	v_add_f32_e32 v190, v190, v234
	v_add_f32_e32 v191, v191, v235
	v_cvt_pk_bf16_f32 v144, v171, v173
	v_cvt_pk_bf16_f32 v145, v179, v180
	v_cvt_pk_bf16_f32 v146, v232, v233
	v_cvt_pk_bf16_f32 v147, v234, v235
	v_exp_f32_e32 v171, v72
	v_exp_f32_e32 v173, v73
	v_exp_f32_e32 v179, v74
	v_exp_f32_e32 v180, v75
	v_exp_f32_e32 v232, v76
	v_exp_f32_e32 v233, v77
	v_exp_f32_e32 v234, v78
	v_exp_f32_e32 v235, v79
	v_add_f32_e32 v190, v190, v171
	v_add_f32_e32 v191, v191, v173
	v_add_f32_e32 v190, v190, v179
	v_add_f32_e32 v191, v191, v180
	v_add_f32_e32 v190, v190, v232
	v_add_f32_e32 v191, v191, v233
	v_add_f32_e32 v190, v190, v234
	v_add_f32_e32 v191, v191, v235
	v_cvt_pk_bf16_f32 v148, v171, v173
	v_cvt_pk_bf16_f32 v149, v179, v180
	v_cvt_pk_bf16_f32 v150, v232, v233
	v_cvt_pk_bf16_f32 v151, v234, v235
	v_exp_f32_e32 v171, v80
	v_exp_f32_e32 v173, v81
	v_exp_f32_e32 v179, v82
	v_exp_f32_e32 v180, v83
	v_exp_f32_e32 v232, v84
	v_exp_f32_e32 v233, v85
	v_exp_f32_e32 v234, v86
	v_exp_f32_e32 v235, v87
	v_add_f32_e32 v190, v190, v171
	v_add_f32_e32 v191, v191, v173
	v_add_f32_e32 v190, v190, v179
	v_add_f32_e32 v191, v191, v180
	v_add_f32_e32 v190, v190, v232
	v_add_f32_e32 v191, v191, v233
	v_add_f32_e32 v190, v190, v234
	v_add_f32_e32 v191, v191, v235
	v_cvt_pk_bf16_f32 v152, v171, v173
	v_cvt_pk_bf16_f32 v153, v179, v180
	v_cvt_pk_bf16_f32 v154, v232, v233
	v_cvt_pk_bf16_f32 v155, v234, v235
	v_exp_f32_e32 v171, v88
	v_exp_f32_e32 v173, v89
	v_exp_f32_e32 v179, v90
	v_exp_f32_e32 v180, v91
	v_exp_f32_e32 v232, v92
	v_exp_f32_e32 v233, v93
	v_exp_f32_e32 v234, v94
	v_exp_f32_e32 v235, v95
	v_add_f32_e32 v190, v190, v171
	v_add_f32_e32 v191, v191, v173
	v_add_f32_e32 v190, v190, v179
	v_add_f32_e32 v191, v191, v180
	v_add_f32_e32 v190, v190, v232
	v_add_f32_e32 v191, v191, v233
	v_add_f32_e32 v190, v190, v234
	v_add_f32_e32 v191, v191, v235
	v_add_f32_e32 v190, v190, v191
	v_cmp_ngt_f32_e32 vcc, 0x71800000, v190
	v_cvt_pk_bf16_f32 v156, v171, v173
	v_cvt_pk_bf16_f32 v157, v179, v180
	v_cvt_pk_bf16_f32 v158, v232, v233
	v_cvt_pk_bf16_f32 v159, v234, v235
	s_nop 0
	s_cbranch_vccnz .Lattn_redo_T30
	v_add_f32_e32 v167, v167, v190
	s_cmp_lg_u32 s14, 0
	s_cbranch_scc1 .Lattn_tb15
	s_cmp_lg_u32 s35, 0
	s_cbranch_scc1 .Lattn_tb15_w6
	s_waitcnt vmcnt(0)
	s_branch .Lattn_tb15_wd

.Lattn_pfq_f:
	v_exp_f32_e32 v180, v99
	v_exp_f32_e32 v232, v100
	v_exp_f32_e32 v233, v101
	v_exp_f32_e32 v234, v102
	v_exp_f32_e32 v235, v103
	v_add_f32_e32 v190, v171, v173
	v_add_f32_e32 v191, v179, v180
	v_add_f32_e32 v190, v190, v232
	v_add_f32_e32 v191, v191, v233
	v_add_f32_e32 v190, v190, v234
	v_add_f32_e32 v191, v191, v235
	v_cvt_pk_bf16_f32 v144, v171, v173
	v_cvt_pk_bf16_f32 v145, v179, v180
	v_cvt_pk_bf16_f32 v146, v232, v233
	v_cvt_pk_bf16_f32 v147, v234, v235
	v_exp_f32_e32 v171, v104
	v_exp_f32_e32 v173, v105
	v_exp_f32_e32 v179, v106
	v_exp_f32_e32 v180, v107
	v_exp_f32_e32 v232, v108
	v_exp_f32_e32 v233, v109
	v_exp_f32_e32 v234, v110
	v_exp_f32_e32 v235, v111
	v_add_f32_e32 v190, v190, v171
	v_add_f32_e32 v191, v191, v173
	v_add_f32_e32 v190, v190, v179
	v_add_f32_e32 v191, v191, v180
	v_add_f32_e32 v190, v190, v232
	v_add_f32_e32 v191, v191, v233
	v_add_f32_e32 v190, v190, v234
	v_add_f32_e32 v191, v191, v235
	v_cvt_pk_bf16_f32 v148, v171, v173
	v_cvt_pk_bf16_f32 v149, v179, v180
	v_cvt_pk_bf16_f32 v150, v232, v233
	v_cvt_pk_bf16_f32 v151, v234, v235
	v_exp_f32_e32 v171, v112
	v_exp_f32_e32 v173, v113
	v_exp_f32_e32 v179, v114
	v_exp_f32_e32 v180, v115
	v_exp_f32_e32 v232, v116
	v_exp_f32_e32 v233, v117
	v_exp_f32_e32 v234, v118
	v_exp_f32_e32 v235, v119
	v_add_f32_e32 v190, v190, v171
	v_add_f32_e32 v191, v191, v173
	v_add_f32_e32 v190, v190, v179
	v_add_f32_e32 v191, v191, v180
	v_add_f32_e32 v190, v190, v232
	v_add_f32_e32 v191, v191, v233
	v_add_f32_e32 v190, v190, v234
	v_add_f32_e32 v191, v191, v235
	v_cvt_pk_bf16_f32 v152, v171, v173
	v_cvt_pk_bf16_f32 v153, v179, v180
	v_cvt_pk_bf16_f32 v154, v232, v233
	v_cvt_pk_bf16_f32 v155, v234, v235
	v_exp_f32_e32 v171, v120
	v_exp_f32_e32 v173, v121
	v_exp_f32_e32 v179, v122
	v_exp_f32_e32 v180, v123
	v_exp_f32_e32 v232, v124
	v_exp_f32_e32 v233, v125
	v_exp_f32_e32 v234, v126
	v_exp_f32_e32 v235, v127
	v_add_f32_e32 v190, v190, v171
	v_add_f32_e32 v191, v191, v173
	v_add_f32_e32 v190, v190, v179
	v_add_f32_e32 v191, v191, v180
	v_add_f32_e32 v190, v190, v232
	v_add_f32_e32 v191, v191, v233
	v_add_f32_e32 v190, v190, v234
	v_add_f32_e32 v191, v191, v235
	v_add_f32_e32 v190, v190, v191
	v_cmp_ngt_f32_e32 vcc, 0x71800000, v190
	v_cvt_pk_bf16_f32 v156, v171, v173
	v_cvt_pk_bf16_f32 v157, v179, v180
	v_cvt_pk_bf16_f32 v158, v232, v233
	v_cvt_pk_bf16_f32 v159, v234, v235
	s_nop 0
	s_cbranch_vccnz .Lattn_redo_T31
	v_add_f32_e32 v167, v167, v190

.Lattn_tb18:
	ds_read_b128 v[216:219], v187 offset:0
	ds_read_b128 v[220:223], v187 offset:4096
	ds_read_b128 v[224:227], v187 offset:8192
	ds_read_b128 v[228:231], v187 offset:12288
	ds_read_b128 v[208:211], v188 offset:0
	ds_read_b128 v[212:215], v188 offset:4096
	v_max3_f32 v254, v64, v65, v66
	s_add_i32 m0, s5, 0
	v_max3_f32 v255, v80, v81, v82
	global_load_lds_dwordx4 v170, s[48:49]
	v_max3_f32 v254, v254, v67, v68
	s_add_i32 m0, s5, 8192
	v_max3_f32 v255, v255, v83, v84
	global_load_lds_dwordx4 v170, s[50:51]
	v_max3_f32 v254, v254, v69, v70
	s_add_i32 m0, s5, 98304
	v_max3_f32 v255, v255, v85, v86
	global_load_lds_dwordx4 v172, s[52:53]
	v_max3_f32 v254, v254, v71, v72
	s_add_i32 m0, s5, 106496
	v_max3_f32 v255, v255, v87, v88
	global_load_lds_dwordx4 v172, s[54:55]
	v_max3_f32 v254, v254, v73, v74
	v_max3_f32 v255, v255, v89, v90
	v_max3_f32 v254, v254, v75, v76
	v_max3_f32 v255, v255, v91, v92
	v_max3_f32 v254, v254, v77, v78
	v_max3_f32 v255, v255, v93, v94
	v_max3_f32 v254, v254, v79, v95
	v_max_f32_e32 v254, v254, v255
	v_mov_b32_e32 v180, 0xc2800000
	v_cmp_lt_f32_e32 vcc, 0x4138aa3b, v254
	v_cmp_gt_f32_e64 s[40:41], v180, v254
	s_nop 4
	s_or_b64 vcc, vcc, s[40:41]
	s_nop 0

.Lattn_tb20:
	ds_read_b128 v[216:219], v187 offset:16384
	ds_read_b128 v[220:223], v187 offset:20480
	ds_read_b128 v[224:227], v187 offset:24576
	ds_read_b128 v[228:231], v187 offset:28672
	ds_read_b128 v[208:211], v188 offset:16384
	ds_read_b128 v[212:215], v188 offset:20480
	v_max3_f32 v254, v96, v97, v98
	s_add_i32 m0, s5, 16384
	v_max3_f32 v255, v112, v113, v114
	global_load_lds_dwordx4 v170, s[48:49]
	v_max3_f32 v254, v254, v99, v100
	s_add_i32 m0, s5, 24576
	v_max3_f32 v255, v255, v115, v116
	global_load_lds_dwordx4 v170, s[50:51]
	v_max3_f32 v254, v254, v101, v102
	s_add_i32 m0, s5, 114688
	v_max3_f32 v255, v255, v117, v118
	global_load_lds_dwordx4 v172, s[52:53]
	v_max3_f32 v254, v254, v103, v104
	s_add_i32 m0, s5, 122880
	v_max3_f32 v255, v255, v119, v120
	global_load_lds_dwordx4 v172, s[54:55]
	v_max3_f32 v254, v254, v105, v106
	v_max3_f32 v255, v255, v121, v122
	v_max3_f32 v254, v254, v107, v108
	v_max3_f32 v255, v255, v123, v124
	v_max3_f32 v254, v254, v109, v110
	v_max3_f32 v255, v255, v125, v126
	v_max3_f32 v254, v254, v111, v127
	v_max_f32_e32 v254, v254, v255
	v_mov_b32_e32 v255, v254
	s_nop 1
	v_permlane32_swap_b32_e32 v254, v255
	v_max_f32_e32 v254, v254, v255
	v_add_f32_e32 v180, 0x4138aa3b, v175
	v_cmp_gt_f32_e32 vcc, v254, v180
	s_nop 1
	v_cndmask_b32_e32 v180, v175, v254, vcc
	v_sub_f32_e32 v255, v175, v180
	v_exp_f32_e32 v174, v255
	v_mov_b32_e32 v175, v180
	v_sub_f32_e32 v96, v96, v175
	v_sub_f32_e32 v97, v97, v175
	v_sub_f32_e32 v98, v98, v175
	v_sub_f32_e32 v99, v99, v175
	v_sub_f32_e32 v100, v100, v175
	v_sub_f32_e32 v101, v101, v175
	v_sub_f32_e32 v102, v102, v175
	v_sub_f32_e32 v103, v103, v175
	v_exp_f32_e32 v96, v96
	v_exp_f32_e32 v97, v97
	v_exp_f32_e32 v98, v98
	v_exp_f32_e32 v99, v99
	v_exp_f32_e32 v100, v100
	v_exp_f32_e32 v101, v101
	v_exp_f32_e32 v102, v102
	v_exp_f32_e32 v103, v103
	v_add_f32_e32 v190, v96, v97
	v_add_f32_e32 v191, v98, v99
	v_add_f32_e32 v190, v190, v100
	v_add_f32_e32 v191, v191, v101
	v_add_f32_e32 v190, v190, v102
	v_add_f32_e32 v191, v191, v103
	v_cvt_pk_bf16_f32 v144, v96, v97
	v_cvt_pk_bf16_f32 v145, v98, v99
	v_cvt_pk_bf16_f32 v146, v100, v101
	v_cvt_pk_bf16_f32 v147, v102, v103
	v_sub_f32_e32 v104, v104, v175
	v_sub_f32_e32 v105, v105, v175
	v_sub_f32_e32 v106, v106, v175
	v_sub_f32_e32 v107, v107, v175
	v_sub_f32_e32 v108, v108, v175
	v_sub_f32_e32 v109, v109, v175
	v_sub_f32_e32 v110, v110, v175
	v_sub_f32_e32 v111, v111, v175
	v_exp_f32_e32 v104, v104
	v_exp_f32_e32 v105, v105
	v_exp_f32_e32 v106, v106
	v_exp_f32_e32 v107, v107
	v_exp_f32_e32 v108, v108
	v_exp_f32_e32 v109, v109
	v_exp_f32_e32 v110, v110
	v_exp_f32_e32 v111, v111
	v_add_f32_e32 v190, v190, v104
	v_add_f32_e32 v191, v191, v105
	v_add_f32_e32 v190, v190, v106
	v_add_f32_e32 v191, v191, v107
	v_add_f32_e32 v190, v190, v108
	v_add_f32_e32 v191, v191, v109
	v_add_f32_e32 v190, v190, v110
	v_add_f32_e32 v191, v191, v111
	v_cvt_pk_bf16_f32 v148, v104, v105
	v_cvt_pk_bf16_f32 v149, v106, v107
	v_cvt_pk_bf16_f32 v150, v108, v109
	v_cvt_pk_bf16_f32 v151, v110, v111
	v_sub_f32_e32 v112, v112, v175
	v_sub_f32_e32 v113, v113, v175
	v_sub_f32_e32 v114, v114, v175
	v_sub_f32_e32 v115, v115, v175
	v_sub_f32_e32 v116, v116, v175
	v_sub_f32_e32 v117, v117, v175
	v_sub_f32_e32 v118, v118, v175
	v_sub_f32_e32 v119, v119, v175
	v_exp_f32_e32 v112, v112
	v_exp_f32_e32 v113, v113
	v_exp_f32_e32 v114, v114
	v_exp_f32_e32 v115, v115
	v_exp_f32_e32 v116, v116
	v_exp_f32_e32 v117, v117
	v_exp_f32_e32 v118, v118
	v_exp_f32_e32 v119, v119
	v_add_f32_e32 v190, v190, v112
	v_add_f32_e32 v191, v191, v113
	v_add_f32_e32 v190, v190, v114
	v_add_f32_e32 v191, v191, v115
	v_add_f32_e32 v190, v190, v116
	v_add_f32_e32 v191, v191, v117
	v_add_f32_e32 v190, v190, v118
	v_add_f32_e32 v191, v191, v119
	v_cvt_pk_bf16_f32 v152, v112, v113
	v_cvt_pk_bf16_f32 v153, v114, v115
	v_cvt_pk_bf16_f32 v154, v116, v117
	v_cvt_pk_bf16_f32 v155, v118, v119
	v_sub_f32_e32 v120, v120, v175
	v_sub_f32_e32 v121, v121, v175
	v_sub_f32_e32 v122, v122, v175
	v_sub_f32_e32 v123, v123, v175
	v_sub_f32_e32 v124, v124, v175
	v_sub_f32_e32 v125, v125, v175
	v_sub_f32_e32 v126, v126, v175
	v_sub_f32_e32 v127, v127, v175
	v_exp_f32_e32 v120, v120
	v_exp_f32_e32 v121, v121
	v_exp_f32_e32 v122, v122
	v_exp_f32_e32 v123, v123
	v_exp_f32_e32 v124, v124
	v_exp_f32_e32 v125, v125
	v_exp_f32_e32 v126, v126
	v_exp_f32_e32 v127, v127
	v_add_f32_e32 v190, v190, v120
	v_add_f32_e32 v191, v191, v121
	v_add_f32_e32 v190, v190, v122
	v_add_f32_e32 v191, v191, v123
	v_add_f32_e32 v190, v190, v124
	v_add_f32_e32 v191, v191, v125
	v_add_f32_e32 v190, v190, v126
	v_add_f32_e32 v191, v191, v127
	v_cvt_pk_bf16_f32 v156, v120, v121
	v_cvt_pk_bf16_f32 v157, v122, v123
	v_cvt_pk_bf16_f32 v158, v124, v125
	v_cvt_pk_bf16_f32 v159, v126, v127
	v_add_f32_e32 v190, v190, v191
	v_fma_f32 v167, v167, v174, v190
	s_cbranch_vccz .Lattn_noresc_L0
	s_nop 7
	s_nop 7
	v_pk_mul_f32 v[0:1], v[0:1], v[174:175] op_sel_hi:[1,0]
	v_pk_mul_f32 v[2:3], v[2:3], v[174:175] op_sel_hi:[1,0]
	v_pk_mul_f32 v[4:5], v[4:5], v[174:175] op_sel_hi:[1,0]
	v_pk_mul_f32 v[6:7], v[6:7], v[174:175] op_sel_hi:[1,0]
	v_pk_mul_f32 v[8:9], v[8:9], v[174:175] op_sel_hi:[1,0]
	v_pk_mul_f32 v[10:11], v[10:11], v[174:175] op_sel_hi:[1,0]
	v_pk_mul_f32 v[12:13], v[12:13], v[174:175] op_sel_hi:[1,0]
	v_pk_mul_f32 v[14:15], v[14:15], v[174:175] op_sel_hi:[1,0]
	v_pk_mul_f32 v[16:17], v[16:17], v[174:175] op_sel_hi:[1,0]
	v_pk_mul_f32 v[18:19], v[18:19], v[174:175] op_sel_hi:[1,0]
	v_pk_mul_f32 v[20:21], v[20:21], v[174:175] op_sel_hi:[1,0]
	v_pk_mul_f32 v[22:23], v[22:23], v[174:175] op_sel_hi:[1,0]
	v_pk_mul_f32 v[24:25], v[24:25], v[174:175] op_sel_hi:[1,0]
	v_pk_mul_f32 v[26:27], v[26:27], v[174:175] op_sel_hi:[1,0]
	v_pk_mul_f32 v[28:29], v[28:29], v[174:175] op_sel_hi:[1,0]
	v_pk_mul_f32 v[30:31], v[30:31], v[174:175] op_sel_hi:[1,0]
	v_pk_mul_f32 v[32:33], v[32:33], v[174:175] op_sel_hi:[1,0]
	v_pk_mul_f32 v[34:35], v[34:35], v[174:175] op_sel_hi:[1,0]
	v_pk_mul_f32 v[36:37], v[36:37], v[174:175] op_sel_hi:[1,0]
	v_pk_mul_f32 v[38:39], v[38:39], v[174:175] op_sel_hi:[1,0]
	v_pk_mul_f32 v[40:41], v[40:41], v[174:175] op_sel_hi:[1,0]
	v_pk_mul_f32 v[42:43], v[42:43], v[174:175] op_sel_hi:[1,0]
	v_pk_mul_f32 v[44:45], v[44:45], v[174:175] op_sel_hi:[1,0]
	v_pk_mul_f32 v[46:47], v[46:47], v[174:175] op_sel_hi:[1,0]
	v_pk_mul_f32 v[48:49], v[48:49], v[174:175] op_sel_hi:[1,0]
	v_pk_mul_f32 v[50:51], v[50:51], v[174:175] op_sel_hi:[1,0]
	v_pk_mul_f32 v[52:53], v[52:53], v[174:175] op_sel_hi:[1,0]
	v_pk_mul_f32 v[54:55], v[54:55], v[174:175] op_sel_hi:[1,0]
	v_pk_mul_f32 v[56:57], v[56:57], v[174:175] op_sel_hi:[1,0]
	v_pk_mul_f32 v[58:59], v[58:59], v[174:175] op_sel_hi:[1,0]
	v_pk_mul_f32 v[60:61], v[60:61], v[174:175] op_sel_hi:[1,0]
	v_pk_mul_f32 v[62:63], v[62:63], v[174:175] op_sel_hi:[1,0]
	s_nop 1

.Lattn_tb22:
	ds_read_b128 v[216:219], v187 offset:32768
	ds_read_b128 v[220:223], v187 offset:36864
	ds_read_b128 v[224:227], v187 offset:40960
	ds_read_b128 v[228:231], v187 offset:45056
	ds_read_b128 v[208:211], v188 offset:32768
	ds_read_b128 v[212:215], v188 offset:36864
	v_max3_f32 v254, v64, v65, v66
	s_add_i32 m0, s5, 32768
	v_max3_f32 v255, v80, v81, v82
	global_load_lds_dwordx4 v170, s[48:49]
	v_max3_f32 v254, v254, v67, v68
	s_add_i32 m0, s5, 40960
	v_max3_f32 v255, v255, v83, v84
	global_load_lds_dwordx4 v170, s[50:51]
	v_max3_f32 v254, v254, v69, v70
	s_add_i32 m0, s5, 65536
	v_max3_f32 v255, v255, v85, v86
	global_load_lds_dwordx4 v172, s[52:53]
	v_max3_f32 v254, v254, v71, v72
	s_add_i32 m0, s5, 73728
	v_max3_f32 v255, v255, v87, v88
	global_load_lds_dwordx4 v172, s[54:55]
	v_max3_f32 v254, v254, v73, v74
	v_max3_f32 v255, v255, v89, v90
	v_max3_f32 v254, v254, v75, v76
	v_max3_f32 v255, v255, v91, v92
	v_max3_f32 v254, v254, v77, v78
	v_max3_f32 v255, v255, v93, v94
	v_max3_f32 v254, v254, v79, v95
	v_max_f32_e32 v254, v254, v255
	v_mov_b32_e32 v255, v254
	s_nop 1
	v_permlane32_swap_b32_e32 v254, v255
	v_max_f32_e32 v254, v254, v255
	v_add_f32_e32 v180, 0x4138aa3b, v175
	v_cmp_gt_f32_e32 vcc, v254, v180
	s_nop 1
	v_cndmask_b32_e32 v180, v175, v254, vcc
	v_sub_f32_e32 v255, v175, v180
	v_exp_f32_e32 v174, v255
	v_mov_b32_e32 v175, v180
	v_sub_f32_e32 v64, v64, v175
	v_sub_f32_e32 v65, v65, v175
	v_sub_f32_e32 v66, v66, v175
	v_sub_f32_e32 v67, v67, v175
	v_sub_f32_e32 v68, v68, v175
	v_sub_f32_e32 v69, v69, v175
	v_sub_f32_e32 v70, v70, v175
	v_sub_f32_e32 v71, v71, v175
	v_exp_f32_e32 v64, v64
	v_exp_f32_e32 v65, v65
	v_exp_f32_e32 v66, v66
	v_exp_f32_e32 v67, v67
	v_exp_f32_e32 v68, v68
	v_exp_f32_e32 v69, v69
	v_exp_f32_e32 v70, v70
	v_exp_f32_e32 v71, v71
	v_add_f32_e32 v190, v64, v65
	v_add_f32_e32 v191, v66, v67
	v_add_f32_e32 v190, v190, v68
	v_add_f32_e32 v191, v191, v69
	v_add_f32_e32 v190, v190, v70
	v_add_f32_e32 v191, v191, v71
	v_cvt_pk_bf16_f32 v144, v64, v65
	v_cvt_pk_bf16_f32 v145, v66, v67
	v_cvt_pk_bf16_f32 v146, v68, v69
	v_cvt_pk_bf16_f32 v147, v70, v71
	v_sub_f32_e32 v72, v72, v175
	v_sub_f32_e32 v73, v73, v175
	v_sub_f32_e32 v74, v74, v175
	v_sub_f32_e32 v75, v75, v175
	v_sub_f32_e32 v76, v76, v175
	v_sub_f32_e32 v77, v77, v175
	v_sub_f32_e32 v78, v78, v175
	v_sub_f32_e32 v79, v79, v175
	v_exp_f32_e32 v72, v72
	v_exp_f32_e32 v73, v73
	v_exp_f32_e32 v74, v74
	v_exp_f32_e32 v75, v75
	v_exp_f32_e32 v76, v76
	v_exp_f32_e32 v77, v77
	v_exp_f32_e32 v78, v78
	v_exp_f32_e32 v79, v79
	v_add_f32_e32 v190, v190, v72
	v_add_f32_e32 v191, v191, v73
	v_add_f32_e32 v190, v190, v74
	v_add_f32_e32 v191, v191, v75
	v_add_f32_e32 v190, v190, v76
	v_add_f32_e32 v191, v191, v77
	v_add_f32_e32 v190, v190, v78
	v_add_f32_e32 v191, v191, v79
	v_cvt_pk_bf16_f32 v148, v72, v73
	v_cvt_pk_bf16_f32 v149, v74, v75
	v_cvt_pk_bf16_f32 v150, v76, v77
	v_cvt_pk_bf16_f32 v151, v78, v79
	v_sub_f32_e32 v80, v80, v175
	v_sub_f32_e32 v81, v81, v175
	v_sub_f32_e32 v82, v82, v175
	v_sub_f32_e32 v83, v83, v175
	v_sub_f32_e32 v84, v84, v175
	v_sub_f32_e32 v85, v85, v175
	v_sub_f32_e32 v86, v86, v175
	v_sub_f32_e32 v87, v87, v175
	v_exp_f32_e32 v80, v80
	v_exp_f32_e32 v81, v81
	v_exp_f32_e32 v82, v82
	v_exp_f32_e32 v83, v83
	v_exp_f32_e32 v84, v84
	v_exp_f32_e32 v85, v85
	v_exp_f32_e32 v86, v86
	v_exp_f32_e32 v87, v87
	v_add_f32_e32 v190, v190, v80
	v_add_f32_e32 v191, v191, v81
	v_add_f32_e32 v190, v190, v82
	v_add_f32_e32 v191, v191, v83
	v_add_f32_e32 v190, v190, v84
	v_add_f32_e32 v191, v191, v85
	v_add_f32_e32 v190, v190, v86
	v_add_f32_e32 v191, v191, v87
	v_cvt_pk_bf16_f32 v152, v80, v81
	v_cvt_pk_bf16_f32 v153, v82, v83
	v_cvt_pk_bf16_f32 v154, v84, v85
	v_cvt_pk_bf16_f32 v155, v86, v87
	v_sub_f32_e32 v88, v88, v175
	v_sub_f32_e32 v89, v89, v175
	v_sub_f32_e32 v90, v90, v175
	v_sub_f32_e32 v91, v91, v175
	v_sub_f32_e32 v92, v92, v175
	v_sub_f32_e32 v93, v93, v175
	v_sub_f32_e32 v94, v94, v175
	v_sub_f32_e32 v95, v95, v175
	v_exp_f32_e32 v88, v88
	v_exp_f32_e32 v89, v89
	v_exp_f32_e32 v90, v90
	v_exp_f32_e32 v91, v91
	v_exp_f32_e32 v92, v92
	v_exp_f32_e32 v93, v93
	v_exp_f32_e32 v94, v94
	v_exp_f32_e32 v95, v95
	v_add_f32_e32 v190, v190, v88
	v_add_f32_e32 v191, v191, v89
	v_add_f32_e32 v190, v190, v90
	v_add_f32_e32 v191, v191, v91
	v_add_f32_e32 v190, v190, v92
	v_add_f32_e32 v191, v191, v93
	v_add_f32_e32 v190, v190, v94
	v_add_f32_e32 v191, v191, v95
	v_cvt_pk_bf16_f32 v156, v88, v89
	v_cvt_pk_bf16_f32 v157, v90, v91
	v_cvt_pk_bf16_f32 v158, v92, v93
	v_cvt_pk_bf16_f32 v159, v94, v95
	v_add_f32_e32 v190, v190, v191
	v_fma_f32 v167, v167, v174, v190
	s_cbranch_vccz .Lattn_noresc_L1
	s_nop 7
	s_nop 7
	v_pk_mul_f32 v[0:1], v[0:1], v[174:175] op_sel_hi:[1,0]
	v_pk_mul_f32 v[2:3], v[2:3], v[174:175] op_sel_hi:[1,0]
	v_pk_mul_f32 v[4:5], v[4:5], v[174:175] op_sel_hi:[1,0]
	v_pk_mul_f32 v[6:7], v[6:7], v[174:175] op_sel_hi:[1,0]
	v_pk_mul_f32 v[8:9], v[8:9], v[174:175] op_sel_hi:[1,0]
	v_pk_mul_f32 v[10:11], v[10:11], v[174:175] op_sel_hi:[1,0]
	v_pk_mul_f32 v[12:13], v[12:13], v[174:175] op_sel_hi:[1,0]
	v_pk_mul_f32 v[14:15], v[14:15], v[174:175] op_sel_hi:[1,0]
	v_pk_mul_f32 v[16:17], v[16:17], v[174:175] op_sel_hi:[1,0]
	v_pk_mul_f32 v[18:19], v[18:19], v[174:175] op_sel_hi:[1,0]
	v_pk_mul_f32 v[20:21], v[20:21], v[174:175] op_sel_hi:[1,0]
	v_pk_mul_f32 v[22:23], v[22:23], v[174:175] op_sel_hi:[1,0]
	v_pk_mul_f32 v[24:25], v[24:25], v[174:175] op_sel_hi:[1,0]
	v_pk_mul_f32 v[26:27], v[26:27], v[174:175] op_sel_hi:[1,0]
	v_pk_mul_f32 v[28:29], v[28:29], v[174:175] op_sel_hi:[1,0]
	v_pk_mul_f32 v[30:31], v[30:31], v[174:175] op_sel_hi:[1,0]
	v_pk_mul_f32 v[32:33], v[32:33], v[174:175] op_sel_hi:[1,0]
	v_pk_mul_f32 v[34:35], v[34:35], v[174:175] op_sel_hi:[1,0]
	v_pk_mul_f32 v[36:37], v[36:37], v[174:175] op_sel_hi:[1,0]
	v_pk_mul_f32 v[38:39], v[38:39], v[174:175] op_sel_hi:[1,0]
	v_pk_mul_f32 v[40:41], v[40:41], v[174:175] op_sel_hi:[1,0]
	v_pk_mul_f32 v[42:43], v[42:43], v[174:175] op_sel_hi:[1,0]
	v_pk_mul_f32 v[44:45], v[44:45], v[174:175] op_sel_hi:[1,0]
	v_pk_mul_f32 v[46:47], v[46:47], v[174:175] op_sel_hi:[1,0]
	v_pk_mul_f32 v[48:49], v[48:49], v[174:175] op_sel_hi:[1,0]
	v_pk_mul_f32 v[50:51], v[50:51], v[174:175] op_sel_hi:[1,0]
	v_pk_mul_f32 v[52:53], v[52:53], v[174:175] op_sel_hi:[1,0]
	v_pk_mul_f32 v[54:55], v[54:55], v[174:175] op_sel_hi:[1,0]
	v_pk_mul_f32 v[56:57], v[56:57], v[174:175] op_sel_hi:[1,0]
	v_pk_mul_f32 v[58:59], v[58:59], v[174:175] op_sel_hi:[1,0]
	v_pk_mul_f32 v[60:61], v[60:61], v[174:175] op_sel_hi:[1,0]
	v_pk_mul_f32 v[62:63], v[62:63], v[174:175] op_sel_hi:[1,0]
	s_nop 1

.Lattn_tb24:
	ds_read_b128 v[216:219], v187 offset:49152
	ds_read_b128 v[220:223], v187 offset:53248
	ds_read_b128 v[224:227], v187 offset:57344
	ds_read_b128 v[228:231], v187 offset:61440
	ds_read_b128 v[208:211], v188 offset:49152
	ds_read_b128 v[212:215], v188 offset:53248
	v_max3_f32 v254, v96, v97, v98
	s_add_i32 m0, s5, 49152
	v_max3_f32 v255, v112, v113, v114
	global_load_lds_dwordx4 v170, s[48:49]
	v_max3_f32 v254, v254, v99, v100
	s_add_i32 m0, s5, 57344
	v_max3_f32 v255, v255, v115, v116
	global_load_lds_dwordx4 v170, s[50:51]
	v_max3_f32 v254, v254, v101, v102
	s_add_i32 m0, s5, 81920
	v_max3_f32 v255, v255, v117, v118
	global_load_lds_dwordx4 v172, s[52:53]
	v_max3_f32 v254, v254, v103, v104
	s_add_i32 m0, s5, 90112
	v_max3_f32 v255, v255, v119, v120
	global_load_lds_dwordx4 v172, s[54:55]
	v_max3_f32 v254, v254, v105, v106
	v_max3_f32 v255, v255, v121, v122
	v_max3_f32 v254, v254, v107, v108
	v_max3_f32 v255, v255, v123, v124
	v_max3_f32 v254, v254, v109, v110
	v_max3_f32 v255, v255, v125, v126
	v_max3_f32 v254, v254, v111, v127
	v_max_f32_e32 v254, v254, v255
	v_mov_b32_e32 v255, v254
	s_nop 1
	v_permlane32_swap_b32_e32 v254, v255
	v_max_f32_e32 v254, v254, v255
	v_add_f32_e32 v180, 0x4138aa3b, v175
	v_cmp_gt_f32_e32 vcc, v254, v180
	s_nop 1
	v_cndmask_b32_e32 v180, v175, v254, vcc
	v_sub_f32_e32 v255, v175, v180
	v_exp_f32_e32 v174, v255
	v_mov_b32_e32 v175, v180
	v_sub_f32_e32 v96, v96, v175
	v_sub_f32_e32 v97, v97, v175
	v_sub_f32_e32 v98, v98, v175
	v_sub_f32_e32 v99, v99, v175
	v_sub_f32_e32 v100, v100, v175
	v_sub_f32_e32 v101, v101, v175
	v_sub_f32_e32 v102, v102, v175
	v_sub_f32_e32 v103, v103, v175
	v_exp_f32_e32 v96, v96
	v_exp_f32_e32 v97, v97
	v_exp_f32_e32 v98, v98
	v_exp_f32_e32 v99, v99
	v_exp_f32_e32 v100, v100
	v_exp_f32_e32 v101, v101
	v_exp_f32_e32 v102, v102
	v_exp_f32_e32 v103, v103
	v_add_f32_e32 v190, v96, v97
	v_add_f32_e32 v191, v98, v99
	v_add_f32_e32 v190, v190, v100
	v_add_f32_e32 v191, v191, v101
	v_add_f32_e32 v190, v190, v102
	v_add_f32_e32 v191, v191, v103
	v_cvt_pk_bf16_f32 v144, v96, v97
	v_cvt_pk_bf16_f32 v145, v98, v99
	v_cvt_pk_bf16_f32 v146, v100, v101
	v_cvt_pk_bf16_f32 v147, v102, v103
	v_sub_f32_e32 v104, v104, v175
	v_sub_f32_e32 v105, v105, v175
	v_sub_f32_e32 v106, v106, v175
	v_sub_f32_e32 v107, v107, v175
	v_sub_f32_e32 v108, v108, v175
	v_sub_f32_e32 v109, v109, v175
	v_sub_f32_e32 v110, v110, v175
	v_sub_f32_e32 v111, v111, v175
	v_exp_f32_e32 v104, v104
	v_exp_f32_e32 v105, v105
	v_exp_f32_e32 v106, v106
	v_exp_f32_e32 v107, v107
	v_exp_f32_e32 v108, v108
	v_exp_f32_e32 v109, v109
	v_exp_f32_e32 v110, v110
	v_exp_f32_e32 v111, v111
	v_add_f32_e32 v190, v190, v104
	v_add_f32_e32 v191, v191, v105
	v_add_f32_e32 v190, v190, v106
	v_add_f32_e32 v191, v191, v107
	v_add_f32_e32 v190, v190, v108
	v_add_f32_e32 v191, v191, v109
	v_add_f32_e32 v190, v190, v110
	v_add_f32_e32 v191, v191, v111
	v_cvt_pk_bf16_f32 v148, v104, v105
	v_cvt_pk_bf16_f32 v149, v106, v107
	v_cvt_pk_bf16_f32 v150, v108, v109
	v_cvt_pk_bf16_f32 v151, v110, v111
	v_sub_f32_e32 v112, v112, v175
	v_sub_f32_e32 v113, v113, v175
	v_sub_f32_e32 v114, v114, v175
	v_sub_f32_e32 v115, v115, v175
	v_sub_f32_e32 v116, v116, v175
	v_sub_f32_e32 v117, v117, v175
	v_sub_f32_e32 v118, v118, v175
	v_sub_f32_e32 v119, v119, v175
	v_exp_f32_e32 v112, v112
	v_exp_f32_e32 v113, v113
	v_exp_f32_e32 v114, v114
	v_exp_f32_e32 v115, v115
	v_exp_f32_e32 v116, v116
	v_exp_f32_e32 v117, v117
	v_exp_f32_e32 v118, v118
	v_exp_f32_e32 v119, v119
	v_add_f32_e32 v190, v190, v112
	v_add_f32_e32 v191, v191, v113
	v_add_f32_e32 v190, v190, v114
	v_add_f32_e32 v191, v191, v115
	v_add_f32_e32 v190, v190, v116
	v_add_f32_e32 v191, v191, v117
	v_add_f32_e32 v190, v190, v118
	v_add_f32_e32 v191, v191, v119
	v_cvt_pk_bf16_f32 v152, v112, v113
	v_cvt_pk_bf16_f32 v153, v114, v115
	v_cvt_pk_bf16_f32 v154, v116, v117
	v_cvt_pk_bf16_f32 v155, v118, v119
	v_sub_f32_e32 v120, v120, v175
	v_sub_f32_e32 v121, v121, v175
	v_sub_f32_e32 v122, v122, v175
	v_sub_f32_e32 v123, v123, v175
	v_sub_f32_e32 v124, v124, v175
	v_sub_f32_e32 v125, v125, v175
	v_sub_f32_e32 v126, v126, v175
	v_sub_f32_e32 v127, v127, v175
	v_exp_f32_e32 v120, v120
	v_exp_f32_e32 v121, v121
	v_exp_f32_e32 v122, v122
	v_exp_f32_e32 v123, v123
	v_exp_f32_e32 v124, v124
	v_exp_f32_e32 v125, v125
	v_exp_f32_e32 v126, v126
	v_exp_f32_e32 v127, v127
	v_add_f32_e32 v190, v190, v120
	v_add_f32_e32 v191, v191, v121
	v_add_f32_e32 v190, v190, v122
	v_add_f32_e32 v191, v191, v123
	v_add_f32_e32 v190, v190, v124
	v_add_f32_e32 v191, v191, v125
	v_add_f32_e32 v190, v190, v126
	v_add_f32_e32 v191, v191, v127
	v_cvt_pk_bf16_f32 v156, v120, v121
	v_cvt_pk_bf16_f32 v157, v122, v123
	v_cvt_pk_bf16_f32 v158, v124, v125
	v_cvt_pk_bf16_f32 v159, v126, v127
	v_add_f32_e32 v190, v190, v191
	v_fma_f32 v167, v167, v174, v190
	s_cbranch_vccz .Lattn_noresc_L2
	s_nop 7
	s_nop 7
	v_pk_mul_f32 v[0:1], v[0:1], v[174:175] op_sel_hi:[1,0]
	v_pk_mul_f32 v[2:3], v[2:3], v[174:175] op_sel_hi:[1,0]
	v_pk_mul_f32 v[4:5], v[4:5], v[174:175] op_sel_hi:[1,0]
	v_pk_mul_f32 v[6:7], v[6:7], v[174:175] op_sel_hi:[1,0]
	v_pk_mul_f32 v[8:9], v[8:9], v[174:175] op_sel_hi:[1,0]
	v_pk_mul_f32 v[10:11], v[10:11], v[174:175] op_sel_hi:[1,0]
	v_pk_mul_f32 v[12:13], v[12:13], v[174:175] op_sel_hi:[1,0]
	v_pk_mul_f32 v[14:15], v[14:15], v[174:175] op_sel_hi:[1,0]
	v_pk_mul_f32 v[16:17], v[16:17], v[174:175] op_sel_hi:[1,0]
	v_pk_mul_f32 v[18:19], v[18:19], v[174:175] op_sel_hi:[1,0]
	v_pk_mul_f32 v[20:21], v[20:21], v[174:175] op_sel_hi:[1,0]
	v_pk_mul_f32 v[22:23], v[22:23], v[174:175] op_sel_hi:[1,0]
	v_pk_mul_f32 v[24:25], v[24:25], v[174:175] op_sel_hi:[1,0]
	v_pk_mul_f32 v[26:27], v[26:27], v[174:175] op_sel_hi:[1,0]
	v_pk_mul_f32 v[28:29], v[28:29], v[174:175] op_sel_hi:[1,0]
	v_pk_mul_f32 v[30:31], v[30:31], v[174:175] op_sel_hi:[1,0]
	v_pk_mul_f32 v[32:33], v[32:33], v[174:175] op_sel_hi:[1,0]
	v_pk_mul_f32 v[34:35], v[34:35], v[174:175] op_sel_hi:[1,0]
	v_pk_mul_f32 v[36:37], v[36:37], v[174:175] op_sel_hi:[1,0]
	v_pk_mul_f32 v[38:39], v[38:39], v[174:175] op_sel_hi:[1,0]
	v_pk_mul_f32 v[40:41], v[40:41], v[174:175] op_sel_hi:[1,0]
	v_pk_mul_f32 v[42:43], v[42:43], v[174:175] op_sel_hi:[1,0]
	v_pk_mul_f32 v[44:45], v[44:45], v[174:175] op_sel_hi:[1,0]
	v_pk_mul_f32 v[46:47], v[46:47], v[174:175] op_sel_hi:[1,0]
	v_pk_mul_f32 v[48:49], v[48:49], v[174:175] op_sel_hi:[1,0]
	v_pk_mul_f32 v[50:51], v[50:51], v[174:175] op_sel_hi:[1,0]
	v_pk_mul_f32 v[52:53], v[52:53], v[174:175] op_sel_hi:[1,0]
	v_pk_mul_f32 v[54:55], v[54:55], v[174:175] op_sel_hi:[1,0]
	v_pk_mul_f32 v[56:57], v[56:57], v[174:175] op_sel_hi:[1,0]
	v_pk_mul_f32 v[58:59], v[58:59], v[174:175] op_sel_hi:[1,0]
	v_pk_mul_f32 v[60:61], v[60:61], v[174:175] op_sel_hi:[1,0]
	v_pk_mul_f32 v[62:63], v[62:63], v[174:175] op_sel_hi:[1,0]
	s_nop 1

.Lattn_tb26:
	ds_read_b128 v[216:219], v187 offset:0
	ds_read_b128 v[220:223], v187 offset:4096
	ds_read_b128 v[224:227], v187 offset:8192
	ds_read_b128 v[228:231], v187 offset:12288
	ds_read_b128 v[208:211], v188 offset:0
	ds_read_b128 v[212:215], v188 offset:4096
	v_max3_f32 v254, v64, v65, v66
	s_add_i32 m0, s5, 0
	v_max3_f32 v255, v80, v81, v82
	global_load_lds_dwordx4 v170, s[48:49]
	v_max3_f32 v254, v254, v67, v68
	s_add_i32 m0, s5, 8192
	v_max3_f32 v255, v255, v83, v84
	global_load_lds_dwordx4 v170, s[50:51]
	v_max3_f32 v254, v254, v69, v70
	s_add_i32 m0, s5, 98304
	v_max3_f32 v255, v255, v85, v86
	global_load_lds_dwordx4 v172, s[52:53]
	v_max3_f32 v254, v254, v71, v72
	s_add_i32 m0, s5, 106496
	v_max3_f32 v255, v255, v87, v88
	global_load_lds_dwordx4 v172, s[54:55]
	v_max3_f32 v254, v254, v73, v74
	v_max3_f32 v255, v255, v89, v90
	v_max3_f32 v254, v254, v75, v76
	v_max3_f32 v255, v255, v91, v92
	v_max3_f32 v254, v254, v77, v78
	v_max3_f32 v255, v255, v93, v94
	v_max3_f32 v254, v254, v79, v95
	v_max_f32_e32 v254, v254, v255
	v_mov_b32_e32 v255, v254
	s_nop 1
	v_permlane32_swap_b32_e32 v254, v255
	v_max_f32_e32 v254, v254, v255
	v_add_f32_e32 v180, 0x4138aa3b, v175
	v_cmp_gt_f32_e32 vcc, v254, v180
	s_nop 1
	v_cndmask_b32_e32 v180, v175, v254, vcc
	v_sub_f32_e32 v255, v175, v180
	v_exp_f32_e32 v174, v255
	v_mov_b32_e32 v175, v180
	v_sub_f32_e32 v64, v64, v175
	v_sub_f32_e32 v65, v65, v175
	v_sub_f32_e32 v66, v66, v175
	v_sub_f32_e32 v67, v67, v175
	v_sub_f32_e32 v68, v68, v175
	v_sub_f32_e32 v69, v69, v175
	v_sub_f32_e32 v70, v70, v175
	v_sub_f32_e32 v71, v71, v175
	v_exp_f32_e32 v64, v64
	v_exp_f32_e32 v65, v65
	v_exp_f32_e32 v66, v66
	v_exp_f32_e32 v67, v67
	v_exp_f32_e32 v68, v68
	v_exp_f32_e32 v69, v69
	v_exp_f32_e32 v70, v70
	v_exp_f32_e32 v71, v71
	v_add_f32_e32 v190, v64, v65
	v_add_f32_e32 v191, v66, v67
	v_add_f32_e32 v190, v190, v68
	v_add_f32_e32 v191, v191, v69
	v_add_f32_e32 v190, v190, v70
	v_add_f32_e32 v191, v191, v71
	v_cvt_pk_bf16_f32 v144, v64, v65
	v_cvt_pk_bf16_f32 v145, v66, v67
	v_cvt_pk_bf16_f32 v146, v68, v69
	v_cvt_pk_bf16_f32 v147, v70, v71
	v_sub_f32_e32 v72, v72, v175
	v_sub_f32_e32 v73, v73, v175
	v_sub_f32_e32 v74, v74, v175
	v_sub_f32_e32 v75, v75, v175
	v_sub_f32_e32 v76, v76, v175
	v_sub_f32_e32 v77, v77, v175
	v_sub_f32_e32 v78, v78, v175
	v_sub_f32_e32 v79, v79, v175
	v_exp_f32_e32 v72, v72
	v_exp_f32_e32 v73, v73
	v_exp_f32_e32 v74, v74
	v_exp_f32_e32 v75, v75
	v_exp_f32_e32 v76, v76
	v_exp_f32_e32 v77, v77
	v_exp_f32_e32 v78, v78
	v_exp_f32_e32 v79, v79
	v_add_f32_e32 v190, v190, v72
	v_add_f32_e32 v191, v191, v73
	v_add_f32_e32 v190, v190, v74
	v_add_f32_e32 v191, v191, v75
	v_add_f32_e32 v190, v190, v76
	v_add_f32_e32 v191, v191, v77
	v_add_f32_e32 v190, v190, v78
	v_add_f32_e32 v191, v191, v79
	v_cvt_pk_bf16_f32 v148, v72, v73
	v_cvt_pk_bf16_f32 v149, v74, v75
	v_cvt_pk_bf16_f32 v150, v76, v77
	v_cvt_pk_bf16_f32 v151, v78, v79
	v_sub_f32_e32 v80, v80, v175
	v_sub_f32_e32 v81, v81, v175
	v_sub_f32_e32 v82, v82, v175
	v_sub_f32_e32 v83, v83, v175
	v_sub_f32_e32 v84, v84, v175
	v_sub_f32_e32 v85, v85, v175
	v_sub_f32_e32 v86, v86, v175
	v_sub_f32_e32 v87, v87, v175
	v_exp_f32_e32 v80, v80
	v_exp_f32_e32 v81, v81
	v_exp_f32_e32 v82, v82
	v_exp_f32_e32 v83, v83
	v_exp_f32_e32 v84, v84
	v_exp_f32_e32 v85, v85
	v_exp_f32_e32 v86, v86
	v_exp_f32_e32 v87, v87
	v_add_f32_e32 v190, v190, v80
	v_add_f32_e32 v191, v191, v81
	v_add_f32_e32 v190, v190, v82
	v_add_f32_e32 v191, v191, v83
	v_add_f32_e32 v190, v190, v84
	v_add_f32_e32 v191, v191, v85
	v_add_f32_e32 v190, v190, v86
	v_add_f32_e32 v191, v191, v87
	v_cvt_pk_bf16_f32 v152, v80, v81
	v_cvt_pk_bf16_f32 v153, v82, v83
	v_cvt_pk_bf16_f32 v154, v84, v85
	v_cvt_pk_bf16_f32 v155, v86, v87
	v_sub_f32_e32 v88, v88, v175
	v_sub_f32_e32 v89, v89, v175
	v_sub_f32_e32 v90, v90, v175
	v_sub_f32_e32 v91, v91, v175
	v_sub_f32_e32 v92, v92, v175
	v_sub_f32_e32 v93, v93, v175
	v_sub_f32_e32 v94, v94, v175
	v_sub_f32_e32 v95, v95, v175
	v_exp_f32_e32 v88, v88
	v_exp_f32_e32 v89, v89
	v_exp_f32_e32 v90, v90
	v_exp_f32_e32 v91, v91
	v_exp_f32_e32 v92, v92
	v_exp_f32_e32 v93, v93
	v_exp_f32_e32 v94, v94
	v_exp_f32_e32 v95, v95
	v_add_f32_e32 v190, v190, v88
	v_add_f32_e32 v191, v191, v89
	v_add_f32_e32 v190, v190, v90
	v_add_f32_e32 v191, v191, v91
	v_add_f32_e32 v190, v190, v92
	v_add_f32_e32 v191, v191, v93
	v_add_f32_e32 v190, v190, v94
	v_add_f32_e32 v191, v191, v95
	v_cvt_pk_bf16_f32 v156, v88, v89
	v_cvt_pk_bf16_f32 v157, v90, v91
	v_cvt_pk_bf16_f32 v158, v92, v93
	v_cvt_pk_bf16_f32 v159, v94, v95
	v_add_f32_e32 v190, v190, v191
	v_fma_f32 v167, v167, v174, v190
	s_cbranch_vccz .Lattn_noresc_L3
	s_nop 7
	s_nop 7
	v_pk_mul_f32 v[0:1], v[0:1], v[174:175] op_sel_hi:[1,0]
	v_pk_mul_f32 v[2:3], v[2:3], v[174:175] op_sel_hi:[1,0]
	v_pk_mul_f32 v[4:5], v[4:5], v[174:175] op_sel_hi:[1,0]
	v_pk_mul_f32 v[6:7], v[6:7], v[174:175] op_sel_hi:[1,0]
	v_pk_mul_f32 v[8:9], v[8:9], v[174:175] op_sel_hi:[1,0]
	v_pk_mul_f32 v[10:11], v[10:11], v[174:175] op_sel_hi:[1,0]
	v_pk_mul_f32 v[12:13], v[12:13], v[174:175] op_sel_hi:[1,0]
	v_pk_mul_f32 v[14:15], v[14:15], v[174:175] op_sel_hi:[1,0]
	v_pk_mul_f32 v[16:17], v[16:17], v[174:175] op_sel_hi:[1,0]
	v_pk_mul_f32 v[18:19], v[18:19], v[174:175] op_sel_hi:[1,0]
	v_pk_mul_f32 v[20:21], v[20:21], v[174:175] op_sel_hi:[1,0]
	v_pk_mul_f32 v[22:23], v[22:23], v[174:175] op_sel_hi:[1,0]
	v_pk_mul_f32 v[24:25], v[24:25], v[174:175] op_sel_hi:[1,0]
	v_pk_mul_f32 v[26:27], v[26:27], v[174:175] op_sel_hi:[1,0]
	v_pk_mul_f32 v[28:29], v[28:29], v[174:175] op_sel_hi:[1,0]
	v_pk_mul_f32 v[30:31], v[30:31], v[174:175] op_sel_hi:[1,0]
	v_pk_mul_f32 v[32:33], v[32:33], v[174:175] op_sel_hi:[1,0]
	v_pk_mul_f32 v[34:35], v[34:35], v[174:175] op_sel_hi:[1,0]
	v_pk_mul_f32 v[36:37], v[36:37], v[174:175] op_sel_hi:[1,0]
	v_pk_mul_f32 v[38:39], v[38:39], v[174:175] op_sel_hi:[1,0]
	v_pk_mul_f32 v[40:41], v[40:41], v[174:175] op_sel_hi:[1,0]
	v_pk_mul_f32 v[42:43], v[42:43], v[174:175] op_sel_hi:[1,0]
	v_pk_mul_f32 v[44:45], v[44:45], v[174:175] op_sel_hi:[1,0]
	v_pk_mul_f32 v[46:47], v[46:47], v[174:175] op_sel_hi:[1,0]
	v_pk_mul_f32 v[48:49], v[48:49], v[174:175] op_sel_hi:[1,0]
	v_pk_mul_f32 v[50:51], v[50:51], v[174:175] op_sel_hi:[1,0]
	v_pk_mul_f32 v[52:53], v[52:53], v[174:175] op_sel_hi:[1,0]
	v_pk_mul_f32 v[54:55], v[54:55], v[174:175] op_sel_hi:[1,0]
	v_pk_mul_f32 v[56:57], v[56:57], v[174:175] op_sel_hi:[1,0]
	v_pk_mul_f32 v[58:59], v[58:59], v[174:175] op_sel_hi:[1,0]
	v_pk_mul_f32 v[60:61], v[60:61], v[174:175] op_sel_hi:[1,0]
	v_pk_mul_f32 v[62:63], v[62:63], v[174:175] op_sel_hi:[1,0]
	s_nop 1

.Lattn_tb28:
	ds_read_b128 v[216:219], v187 offset:16384
	ds_read_b128 v[220:223], v187 offset:20480
	ds_read_b128 v[224:227], v187 offset:24576
	ds_read_b128 v[228:231], v187 offset:28672
	ds_read_b128 v[208:211], v188 offset:16384
	ds_read_b128 v[212:215], v188 offset:20480
	v_max3_f32 v254, v96, v97, v98
	s_add_i32 m0, s5, 114688
	v_max3_f32 v255, v112, v113, v114
	global_load_lds_dwordx4 v172, s[52:53]
	v_max3_f32 v254, v254, v99, v100
	s_add_i32 m0, s5, 122880
	v_max3_f32 v255, v255, v115, v116
	global_load_lds_dwordx4 v172, s[54:55]
	v_max3_f32 v254, v254, v101, v102
	v_max3_f32 v255, v255, v117, v118
	v_max3_f32 v254, v254, v103, v104
	v_max3_f32 v255, v255, v119, v120
	v_max3_f32 v254, v254, v105, v106
	v_max3_f32 v255, v255, v121, v122
	v_max3_f32 v254, v254, v107, v108
	v_max3_f32 v255, v255, v123, v124
	v_max3_f32 v254, v254, v109, v110
	v_max3_f32 v255, v255, v125, v126
	v_max3_f32 v254, v254, v111, v127
	v_max_f32_e32 v254, v254, v255
	v_mov_b32_e32 v255, v254
	s_nop 1
	v_permlane32_swap_b32_e32 v254, v255
	v_max_f32_e32 v254, v254, v255
	v_add_f32_e32 v180, 0x4138aa3b, v175
	v_cmp_gt_f32_e32 vcc, v254, v180
	s_nop 1
	v_cndmask_b32_e32 v180, v175, v254, vcc
	v_sub_f32_e32 v255, v175, v180
	v_exp_f32_e32 v174, v255
	v_mov_b32_e32 v175, v180
	v_sub_f32_e32 v96, v96, v175
	v_sub_f32_e32 v97, v97, v175
	v_sub_f32_e32 v98, v98, v175
	v_sub_f32_e32 v99, v99, v175
	v_sub_f32_e32 v100, v100, v175
	v_sub_f32_e32 v101, v101, v175
	v_sub_f32_e32 v102, v102, v175
	v_sub_f32_e32 v103, v103, v175
	v_exp_f32_e32 v96, v96
	v_exp_f32_e32 v97, v97
	v_exp_f32_e32 v98, v98
	v_exp_f32_e32 v99, v99
	v_exp_f32_e32 v100, v100
	v_exp_f32_e32 v101, v101
	v_exp_f32_e32 v102, v102
	v_exp_f32_e32 v103, v103
	v_add_f32_e32 v190, v96, v97
	v_add_f32_e32 v191, v98, v99
	v_add_f32_e32 v190, v190, v100
	v_add_f32_e32 v191, v191, v101
	v_add_f32_e32 v190, v190, v102
	v_add_f32_e32 v191, v191, v103
	v_cvt_pk_bf16_f32 v144, v96, v97
	v_cvt_pk_bf16_f32 v145, v98, v99
	v_cvt_pk_bf16_f32 v146, v100, v101
	v_cvt_pk_bf16_f32 v147, v102, v103
	v_sub_f32_e32 v104, v104, v175
	v_sub_f32_e32 v105, v105, v175
	v_sub_f32_e32 v106, v106, v175
	v_sub_f32_e32 v107, v107, v175
	v_sub_f32_e32 v108, v108, v175
	v_sub_f32_e32 v109, v109, v175
	v_sub_f32_e32 v110, v110, v175
	v_sub_f32_e32 v111, v111, v175
	v_exp_f32_e32 v104, v104
	v_exp_f32_e32 v105, v105
	v_exp_f32_e32 v106, v106
	v_exp_f32_e32 v107, v107
	v_exp_f32_e32 v108, v108
	v_exp_f32_e32 v109, v109
	v_exp_f32_e32 v110, v110
	v_exp_f32_e32 v111, v111
	v_add_f32_e32 v190, v190, v104
	v_add_f32_e32 v191, v191, v105
	v_add_f32_e32 v190, v190, v106
	v_add_f32_e32 v191, v191, v107
	v_add_f32_e32 v190, v190, v108
	v_add_f32_e32 v191, v191, v109
	v_add_f32_e32 v190, v190, v110
	v_add_f32_e32 v191, v191, v111
	v_cvt_pk_bf16_f32 v148, v104, v105
	v_cvt_pk_bf16_f32 v149, v106, v107
	v_cvt_pk_bf16_f32 v150, v108, v109
	v_cvt_pk_bf16_f32 v151, v110, v111
	v_sub_f32_e32 v112, v112, v175
	v_sub_f32_e32 v113, v113, v175
	v_sub_f32_e32 v114, v114, v175
	v_sub_f32_e32 v115, v115, v175
	v_sub_f32_e32 v116, v116, v175
	v_sub_f32_e32 v117, v117, v175
	v_sub_f32_e32 v118, v118, v175
	v_sub_f32_e32 v119, v119, v175
	v_exp_f32_e32 v112, v112
	v_exp_f32_e32 v113, v113
	v_exp_f32_e32 v114, v114
	v_exp_f32_e32 v115, v115
	v_exp_f32_e32 v116, v116
	v_exp_f32_e32 v117, v117
	v_exp_f32_e32 v118, v118
	v_exp_f32_e32 v119, v119
	v_add_f32_e32 v190, v190, v112
	v_add_f32_e32 v191, v191, v113
	v_add_f32_e32 v190, v190, v114
	v_add_f32_e32 v191, v191, v115
	v_add_f32_e32 v190, v190, v116
	v_add_f32_e32 v191, v191, v117
	v_add_f32_e32 v190, v190, v118
	v_add_f32_e32 v191, v191, v119
	v_cvt_pk_bf16_f32 v152, v112, v113
	v_cvt_pk_bf16_f32 v153, v114, v115
	v_cvt_pk_bf16_f32 v154, v116, v117
	v_cvt_pk_bf16_f32 v155, v118, v119
	v_sub_f32_e32 v120, v120, v175
	v_sub_f32_e32 v121, v121, v175
	v_sub_f32_e32 v122, v122, v175
	v_sub_f32_e32 v123, v123, v175
	v_sub_f32_e32 v124, v124, v175
	v_sub_f32_e32 v125, v125, v175
	v_sub_f32_e32 v126, v126, v175
	v_sub_f32_e32 v127, v127, v175
	v_exp_f32_e32 v120, v120
	v_exp_f32_e32 v121, v121
	v_exp_f32_e32 v122, v122
	v_exp_f32_e32 v123, v123
	v_exp_f32_e32 v124, v124
	v_exp_f32_e32 v125, v125
	v_exp_f32_e32 v126, v126
	v_exp_f32_e32 v127, v127
	v_add_f32_e32 v190, v190, v120
	v_add_f32_e32 v191, v191, v121
	v_add_f32_e32 v190, v190, v122
	v_add_f32_e32 v191, v191, v123
	v_add_f32_e32 v190, v190, v124
	v_add_f32_e32 v191, v191, v125
	v_add_f32_e32 v190, v190, v126
	v_add_f32_e32 v191, v191, v127
	v_cvt_pk_bf16_f32 v156, v120, v121
	v_cvt_pk_bf16_f32 v157, v122, v123
	v_cvt_pk_bf16_f32 v158, v124, v125
	v_cvt_pk_bf16_f32 v159, v126, v127
	v_add_f32_e32 v190, v190, v191
	v_fma_f32 v167, v167, v174, v190
	s_cbranch_vccz .Lattn_noresc_T29
	s_nop 7
	s_nop 7
	v_pk_mul_f32 v[0:1], v[0:1], v[174:175] op_sel_hi:[1,0]
	v_pk_mul_f32 v[2:3], v[2:3], v[174:175] op_sel_hi:[1,0]
	v_pk_mul_f32 v[4:5], v[4:5], v[174:175] op_sel_hi:[1,0]
	v_pk_mul_f32 v[6:7], v[6:7], v[174:175] op_sel_hi:[1,0]
	v_pk_mul_f32 v[8:9], v[8:9], v[174:175] op_sel_hi:[1,0]
	v_pk_mul_f32 v[10:11], v[10:11], v[174:175] op_sel_hi:[1,0]
	v_pk_mul_f32 v[12:13], v[12:13], v[174:175] op_sel_hi:[1,0]
	v_pk_mul_f32 v[14:15], v[14:15], v[174:175] op_sel_hi:[1,0]
	v_pk_mul_f32 v[16:17], v[16:17], v[174:175] op_sel_hi:[1,0]
	v_pk_mul_f32 v[18:19], v[18:19], v[174:175] op_sel_hi:[1,0]
	v_pk_mul_f32 v[20:21], v[20:21], v[174:175] op_sel_hi:[1,0]
	v_pk_mul_f32 v[22:23], v[22:23], v[174:175] op_sel_hi:[1,0]
	v_pk_mul_f32 v[24:25], v[24:25], v[174:175] op_sel_hi:[1,0]
	v_pk_mul_f32 v[26:27], v[26:27], v[174:175] op_sel_hi:[1,0]
	v_pk_mul_f32 v[28:29], v[28:29], v[174:175] op_sel_hi:[1,0]
	v_pk_mul_f32 v[30:31], v[30:31], v[174:175] op_sel_hi:[1,0]
	v_pk_mul_f32 v[32:33], v[32:33], v[174:175] op_sel_hi:[1,0]
	v_pk_mul_f32 v[34:35], v[34:35], v[174:175] op_sel_hi:[1,0]
	v_pk_mul_f32 v[36:37], v[36:37], v[174:175] op_sel_hi:[1,0]
	v_pk_mul_f32 v[38:39], v[38:39], v[174:175] op_sel_hi:[1,0]
	v_pk_mul_f32 v[40:41], v[40:41], v[174:175] op_sel_hi:[1,0]
	v_pk_mul_f32 v[42:43], v[42:43], v[174:175] op_sel_hi:[1,0]
	v_pk_mul_f32 v[44:45], v[44:45], v[174:175] op_sel_hi:[1,0]
	v_pk_mul_f32 v[46:47], v[46:47], v[174:175] op_sel_hi:[1,0]
	v_pk_mul_f32 v[48:49], v[48:49], v[174:175] op_sel_hi:[1,0]
	v_pk_mul_f32 v[50:51], v[50:51], v[174:175] op_sel_hi:[1,0]
	v_pk_mul_f32 v[52:53], v[52:53], v[174:175] op_sel_hi:[1,0]
	v_pk_mul_f32 v[54:55], v[54:55], v[174:175] op_sel_hi:[1,0]
	v_pk_mul_f32 v[56:57], v[56:57], v[174:175] op_sel_hi:[1,0]
	v_pk_mul_f32 v[58:59], v[58:59], v[174:175] op_sel_hi:[1,0]
	v_pk_mul_f32 v[60:61], v[60:61], v[174:175] op_sel_hi:[1,0]
	v_pk_mul_f32 v[62:63], v[62:63], v[174:175] op_sel_hi:[1,0]
	s_nop 1
